# MoBA/FoX: fused A+B sub-tile bodies (QK of both tiles back to back, exp and row sums under the other tile MFMAs); FoX: forget-sample prefetch, F scale deferred, accumulator starts at fm-fs
# speedup vs baseline: 1.0389x; 1.0176x over previous
; template <int MODE>
; DI void attn_wg2_item(const bf16_t* Qm, const bf16_t* Km, const bf16_t* Vtm, const float* Fb, const float* KMPb, const bf16_t* G, bf16_t* Y, int bh, int qb2, int halfq, int mixer, float Mb, LAS unsigned char* lds, int tid, int wave, int lane) {
;     ...
;     const int qtA = halfq ? qb2 * 8 + wave : qb2 * 16 + wave, qtB = halfq ? -1 : qb2 * 16 + 15 - wave, tA = qtA * 32 + r, tB = halfq ? tA : qtB * 32 + r;
;     bf16x8 qfA[4], qfB[4];
;     load_q(qfA, Qm + ((size_t)bh * S + tA) * 64 + 8 * h);
;     load_q(qfB, Qm + ((size_t)bh * S + tB) * 64 + 8 * h);
;     const int qblkA = qtA >> 3, qblkB = halfq ? 0 : (qtB >> 3);
;     unsigned selA = 0u, selB = 0u, visA = 0xffffffffu, visB = 0xffffffffu;
;     float fmA = 0.f, fmB = 0.f, Ft0 = 0.f;
;     if (MODE == 3) { fmA = (Fb[tA] - Mb) * LOG2E; fmB = (Fb[tB] - Mb) * LOG2E; Ft0 = Fb[halfq ? qb2 * 256 : qb2 * 512]; }
;     if (MODE == 2) {
;         selA = moba_select(KMPb, qfA, qblkA, r, h); selB = halfq ? 0u : moba_select(KMPb, qfB, qblkB, r, h);
;         visA = wave_or(selA) | (1u << qblkA); visB = wave_or(selB) | (1u << qblkB);
;     }
;     f32x16 oA0, oA1, oB0, oB1;
; #pragma unroll
;     for (int i = 0; i < 16; ++i) { oA0[i] = 0.f; oA1[i] = 0.f; oB0[i] = 0.f; oB1[i] = 0.f; }
;     float lA = 0.f, lB = 0.f;
;     const float mb2 = -Mb * LOG2E, NEGI = -__builtin_inff();
;     const int srow = tid >> 3, sch = tid & 7;
;     const bf16_t* kg = Km + ((size_t)bh * S + srow) * 64 + sch * 8;
;     const bf16_t* vg = Vtm + ((size_t)bh * 64 + srow) * S + sch * 8;
; __global__ void __launch_bounds__(512, 2) mega_fwd(Args a) {
;     ...
;                     for (;;) {
;                         if (tid == 0) *qw = (int)atomicAdd(ctr, 1u);
;                         __syncthreads();
;                         const int idx = __builtin_amdgcn_readfirstlane(*qw);
;                         __syncthreads();
;                         if (idx >= 72) break;
;                         const int k = idx >> 2, j = idx & 3, bh = 2 * q + (j >> 1), halfq = (k >= 6 && k < 10), qb2 = k < 6 ? 13 - k : (halfq ? 37 - k : 17 - k);
;                         if (j & 1) attn_wg2_item<3>(Qb + (size_t)3 * 16 * S * 64, Kb + (size_t)3 * 16 * S * 64, VT + (size_t)3 * 16 * 64 * S, FB + (size_t)bh * S, nullptr, Gb, Yb, bh, qb2, halfq, 3, Mx[2], lds, tid, wave, lane);
.LBB0_316:
	s_or_b64 exec, exec, s[0:1]
	v_mov_b32_e32 v0, s86
	s_waitcnt lgkmcnt(0)
	s_barrier
	ds_read_b32 v0, v0
	s_mov_b64 s[0:1], -1
	s_waitcnt lgkmcnt(0)
	s_barrier
	v_readfirstlane_b32 s4, v0
	s_cmpk_gt_i32 s4, 0x47
	s_cbranch_scc1 .LBB0_311
	s_ashr_i32 s5, s4, 2
	s_bfe_u32 s0, s4, 0x10001
	s_or_b32 s83, s0, s82
	s_add_i32 s0, s5, -10
	s_cmp_lt_u32 s0, -4
	s_cselect_b64 s[10:11], -1, 0
	s_and_b64 s[0:1], s[10:11], exec
	s_cselect_b32 s0, 17, 37
	s_cmp_gt_i32 s5, 5
	s_cselect_b32 s0, s0, 13
	s_sub_i32 s68, s0, s5
	s_bitcmp0_b32 s4, 0
	s_cbranch_scc1 .LBB0_356
	s_lshl_b32 s50, s83, 13
	s_lshl_b32 s0, s83, 15
	s_add_u32 s0, s71, s0
	s_addc_u32 s1, s72, 0
	s_lshl_b32 s12, s68, 3
	s_lshl_b32 s13, s68, 4
	s_and_b64 s[4:5], s[10:11], exec
	v_mov_b32_e32 v7, v165
	v_mov_b32_e32 v5, v178
	s_cselect_b32 s69, s13, s12
	v_readlane_b32 s4, v254, 44
	s_add_i32 s69, s69, s4
	v_and_b32_e32 v4, 31, v5
	s_sub_i32 s4, s13, s4
	s_add_i32 s13, s4, 15
	v_lshl_or_b32 v168, s69, 5, v4
	v_ashrrev_i32_e32 v6, 5, v5
	s_and_b64 s[4:5], s[10:11], exec
	v_ashrrev_i32_e32 v169, 31, v168
	s_cselect_b32 s84, s13, -1
	v_lshl_add_u64 v[2:3], s[50:51], 0, v[168:169]
	v_lshlrev_b32_e32 v160, 3, v6
	v_lshl_or_b32 v0, s84, 5, v4
	v_lshlrev_b64 v[2:3], 7, v[2:3]
	v_ashrrev_i32_e32 v161, 31, v160
	v_cndmask_b32_e64 v166, v168, v0, s[10:11]
	v_lshl_add_u64 v[2:3], s[60:61], 0, v[2:3]
	v_lshlrev_b64 v[8:9], 1, v[160:161]
	v_lshl_add_u64 v[2:3], v[2:3], 0, v[8:9]
	v_ashrrev_i32_e32 v167, 31, v166
	global_load_dwordx4 v[96:99], v[2:3], off
	global_load_dwordx4 v[100:103], v[2:3], off offset:32
	global_load_dwordx4 v[104:107], v[2:3], off offset:64
	global_load_dwordx4 v[108:111], v[2:3], off offset:96
	v_lshl_add_u64 v[2:3], s[50:51], 0, v[166:167]
	s_cselect_b32 s4, 9, 8
	v_lshlrev_b64 v[2:3], 7, v[2:3]
	s_lshl_b32 s4, s68, s4
	s_mov_b32 s5, s51
	v_lshl_add_u64 v[2:3], s[60:61], 0, v[2:3]
	s_lshl_b64 s[4:5], s[4:5], 2
	v_lshl_add_u64 v[2:3], v[2:3], 0, v[8:9]
	s_add_u32 s4, s0, s4
	global_load_dwordx4 v[112:115], v[2:3], off
	global_load_dwordx4 v[116:119], v[2:3], off offset:32
	global_load_dwordx4 v[120:123], v[2:3], off offset:64
	global_load_dwordx4 v[124:127], v[2:3], off offset:96
	v_lshl_add_u64 v[2:3], v[168:169], 2, s[0:1]
	s_addc_u32 s5, s1, s5
	global_load_dword v8, v[2:3], off
	global_load_dword v163, v1, s[4:5]
	v_lshl_add_u64 v[2:3], v[166:167], 2, s[0:1]
	global_load_dword v9, v[2:3], off
	v_ashrrev_i32_e32 v2, 3, v7
	v_ashrrev_i32_e32 v3, 31, v2
	v_lshl_add_u64 v[10:11], s[50:51], 0, v[2:3]
	v_lshlrev_b64 v[10:11], 7, v[10:11]
	v_lshlrev_b32_e32 v186, 4, v7
	s_lshl_b32 s4, s83, 20
	v_lshl_add_u64 v[10:11], s[52:53], 0, v[10:11]
	v_and_b32_e32 v0, 0x70, v186
	s_add_u32 s4, s76, s4
	v_lshl_add_u64 v[170:171], v[10:11], 0, v[0:1]
	s_addc_u32 s5, s77, 0
	v_lshlrev_b64 v[10:11], 14, v[2:3]
	v_lshl_add_u64 v[10:11], s[4:5], 0, v[10:11]
	v_mad_u64_u32 v[174:175], s[4:5], v2, s91, v[0:1]
	s_lshl_b32 s4, s68, 2
	s_or_b32 s13, s4, 3
	s_or_b32 s12, s12, 7
	s_and_b64 s[4:5], s[10:11], exec
	s_cselect_b32 s64, s12, s13
	s_mov_b32 s65, s51
	s_lshl_b64 s[4:5], s[64:65], 13
	v_lshl_add_u64 v[172:173], v[10:11], 0, v[0:1]
	v_lshl_add_u64 v[2:3], v[170:171], 0, s[4:5]
	s_lshl_b32 s50, s64, 6
	s_lshl_b64 s[14:15], s[50:51], 2
	s_add_u32 s14, s0, s14
	s_addc_u32 s15, s1, s15
	global_load_dword v216, v1, s[14:15] offset:-4
	global_load_dwordx4 v[10:13], v[2:3], off
	v_lshl_add_u64 v[2:3], s[50:51], 1, v[172:173]
	global_load_dwordx4 v[14:17], v[2:3], off
	v_add_u32_e32 v0, 0, v174
	v_cmp_gt_i32_e64 s[12:13], 16, v7
	v_cmp_lt_i32_e32 vcc, 15, v7
	s_waitcnt vmcnt(1)
	ds_write_b128 v0, v[10:13]
	s_waitcnt vmcnt(0)
	ds_write_b128 v0, v[14:17] offset:9216
	v_lshlrev_b32_e32 v0, 2, v7
	s_and_saveexec_b64 s[4:5], vcc
	s_xor_b64 s[4:5], exec, s[4:5]
	v_lshlrev_b32_e32 v186, 4, v7
	v_mov_b64_e32 v[2:3], v[0:1]
	s_andn2_saveexec_b64 s[4:5], s[4:5]
	s_cbranch_execz .LBB0_322
	s_lshl_b64 s[14:15], s[50:51], 2
	s_add_u32 s14, s0, s14
	s_addc_u32 s15, s1, s15
	v_ashrrev_i32_e32 v3, 31, v0
	v_mov_b32_e32 v2, v0
	v_lshl_add_u64 v[10:11], v[2:3], 2, s[14:15]
	global_load_dwordx4 v[10:13], v[10:11], off
	s_mov_b32 s14, 0x3fb8aa3b
	v_add_u32_e32 v0, 0, v186
	s_waitcnt vmcnt(0)
	v_pk_mul_f32 v[12:13], v[12:13], s[14:15] op_sel_hi:[1,0]
	v_pk_mul_f32 v[10:11], v[10:11], s[14:15] op_sel_hi:[1,0]
	ds_write_b128 v0, v[10:13] offset:18432

; template <int MODE>
; DI void attn_wg2_item(const bf16_t* Qm, const bf16_t* Km, const bf16_t* Vtm, const float* Fb, const float* KMPb, const bf16_t* G, bf16_t* Y, int bh, int qb2, int halfq, int mixer, float Mb, LAS unsigned char* lds, int tid, int wave, int lane) {
;     ...
;         int nxt = cur - 1;
;         if (MODE == 3) { if (nxt >= 0) { const float fk = Fb[nxt * 64 + 63]; if ((Ft0 - fk) + 2.0f * Mb < -104.0f) nxt = -1; } }
;         nxt = __builtin_amdgcn_readfirstlane(nxt);
;         bf16x8 kreg; u32x4 vreg; f32x4 freg;
; #pragma unroll
;         for (int e = 0; e < 8; ++e) kreg[e] = 0;
;         vreg = (u32x4){0u, 0u, 0u, 0u}; freg = (f32x4){0.f, 0.f, 0.f, 0.f};
;         if (nxt >= 0) {
;             kreg = *(const bf16x8*)(kg + (size_t)nxt * 4096);
;             vreg = *(const u32x4*)(vg + nxt * 64);
;             if (MODE == 3 && tid < 16) freg = *(const f32x4*)(Fb + nxt * 64 + tid * 4);
;         }
.LBB0_325:
	s_add_i32 s48, s64, -1
	s_lshl_b32 s50, s48, 6
	s_lshl_b64 s[4:5], s[50:51], 2
	s_add_u32 s4, s0, s4
	s_addc_u32 s5, s1, s5
	s_waitcnt vmcnt(0)
	v_sub_f32_e32 v0, v163, v216
	global_load_dword v216, v1, s[4:5] offset:-4
	s_mov_b32 s4, 0xc2d00000
	v_add_f32_e32 v0, v182, v0
	v_cmp_ngt_f32_e32 vcc, s4, v0
	v_mov_b32_e32 v0, s48
	s_nop 0
	v_cndmask_b32_e32 v0, -1, v0, vcc
.LBB0_326:
	s_nop 0
	v_readfirstlane_b32 s4, v0
	s_cmp_gt_i32 s4, -1
	s_cselect_b64 s[62:63], -1, 0
	s_cmp_lt_i32 s4, 0
	s_cselect_b64 s[48:49], -1, 0
	s_and_b64 vcc, exec, s[48:49]
	s_cbranch_vccnz .LBB0_330
	s_mov_b32 s5, s51
	s_lshl_b64 s[66:67], s[4:5], 13
	v_lshl_add_u64 v[2:3], v[170:171], 0, s[66:67]
	s_lshl_b32 s50, s4, 6
	v_lshl_add_u64 v[4:5], s[50:51], 1, v[172:173]
	global_load_dwordx4 v[6:9], v[2:3], off
	global_load_dwordx4 v[10:13], v[4:5], off
	v_mov_b32_e32 v5, 0
	v_mov_b32_e32 v4, 0
	v_mov_b32_e32 v3, 0
	v_mov_b32_e32 v2, 0
	s_and_saveexec_b64 s[66:67], s[12:13]
	s_cbranch_execz .LBB0_329
	v_lshl_add_u64 v[2:3], s[50:51], 2, v[176:177]
	global_load_dwordx4 v[2:5], v[2:3], off
.LBB0_329:
	s_or_b64 exec, exec, s[66:67]
	s_branch .LBB0_331

; template <int MODE>
; DI void sub_tile(const bf16x8 (&kf)[4], const bf16x8 (&vf)[2][2], const bf16x8 (&qf)[4], f32x16& o0, f32x16& o1, float& l, bool diag, float offs, float fm, const LAS float* fsp, int r, int h) {
;     f32x16 x;
;     float p[16];
;     if (MODE == 2) {
; #pragma unroll
;         for (int i = 0; i < 16; ++i) x[i] = offs;
; #pragma unroll
;         for (int sp = 0; sp < 4; ++sp) x = mfma32(kf[sp], qf[sp], x);
; #pragma unroll
;         for (int i = 0; i < 16; ++i) p[i] = ex2(x[i]);
;     } else {
;         x = qk_tile(kf, qf);
; #pragma unroll
;         for (int g = 0; g < 4; ++g) {
;             const f32x4 fs = *(const LAS f32x4*)(fsp + 16 * (g >> 1) + 8 * h + 4 * (g & 1));
; #pragma unroll
;             for (int e = 0; e < 4; ++e) p[4 * g + e] = ex2(x[4 * g + e] + (fm - fs[e]));
;         }
;     }
;     if (diag) {
; #pragma unroll
;         for (int i = 0; i < 16; ++i) if (kidx(i, h) > r) p[i] = 0.f;
;     }
; #pragma unroll
; template <int MODE>
; DI void attn_wg2_item(const bf16_t* Qm, const bf16_t* Km, const bf16_t* Vtm, const float* Fb, const float* KMPb, const bf16_t* G, bf16_t* Y, int bh, int qb2, int halfq, int mixer, float Mb, LAS unsigned char* lds, int tid, int wave, int lane) {
;     ...
;             const int tau = cur * 2 + kk, nb = tau >> 3;
;             bool actA = tau <= qtA, actB = tau <= qtB;
;             if (MODE == 2) { actA = actA && ((visA >> nb) & 1u); actB = actB && ((visB >> nb) & 1u); }
;             if (actA || actB) {
;                 bf16x8 kf[4], vf[2][2];
; #pragma unroll
;                 for (int sp = 0; sp < 4; ++sp) kf[sp] = *(LAS bf16x8*)(lb + kra + kk * 32 * 144 + sp * 32);
; #pragma unroll
;                 for (int dd = 0; dd < 2; ++dd)
; #pragma unroll
;                     for (int s = 0; s < 2; ++s) vf[dd][s] = *(LAS bf16x8*)(lb + vra + dd * 32 * 144 + kk * 64 + s * 32);
;                 float offA = mb2, offB = mb2;
;                 if (MODE == 2) { offA = ((nb == qblkA) || ((selA >> nb) & 1u)) ? mb2 : NEGI; offB = ((nb == qblkB) || ((selB >> nb) & 1u)) ? mb2 : NEGI; }
;                 const LAS float* fsp = (const LAS float*)(lb + AW_F) + kk * 32;
;                 if (actA) sub_tile<MODE>(kf, vf, qfA, oA0, oA1, lA, tau == qtA, offA, fmA, fsp, r, h);
;                 if (actB) sub_tile<MODE>(kf, vf, qfB, oB0, oB1, lB, tau == qtB, offB, fmB, fsp, r, h);
.LBB0_331:
	s_mul_i32 s5, s85, 0x4900
	s_add_i32 s50, s5, 0
	s_lshl_b32 s5, s64, 1
	s_cmp_lt_i32 s5, s69
	s_cselect_b64 s[66:67], -1, 0
	s_cmp_lt_i32 s5, s84
	s_cselect_b64 s[64:65], -1, 0
	v_add_u32_e32 v0, s50, v192
	v_add_u32_e32 v15, s50, v196
	s_or_b64 s[78:79], s[66:67], s[64:65]
	s_andn2_b64 vcc, exec, s[78:79]
	v_add_u32_e32 v14, v0, v194
	v_add_u32_e32 v0, v15, v194
	s_cbranch_vccnz .LBB0_340
	ds_read_b128 v[144:147], v14 offset:4608
	ds_read_b128 v[148:151], v14 offset:4640
	ds_read_b128 v[152:155], v14 offset:4672
	ds_read_b128 v[156:159], v14 offset:4704
	ds_read_b128 v[140:143], v0 offset:9280
	ds_read_b128 v[136:139], v0 offset:9312
	ds_read_b128 v[132:135], v0 offset:13888
	ds_read_b128 v[128:131], v0 offset:13920
	s_and_b64 s[78:79], s[66:67], s[64:65]
	s_cbranch_scc0 .Lfox_nf1
	s_or_b32 s78, s5, 1
	s_cmp_eq_u32 s78, s69
	s_cbranch_scc1 .Lfox_nf1
	s_cmp_eq_u32 s78, s84
	s_cbranch_scc1 .Lfox_nf1
	v_add_u32_e32 v179, s50, v197
	ds_read_b128 v[200:203], v179 offset:18560
	ds_read_b128 v[204:207], v179 offset:18576
	ds_read_b128 v[208:211], v179 offset:18624
	ds_read_b128 v[212:215], v179 offset:18640
	s_waitcnt lgkmcnt(0)
	v_sub_f32_e32 v80, v188, v200
	v_sub_f32_e32 v81, v188, v201
	v_sub_f32_e32 v82, v188, v202
	v_sub_f32_e32 v83, v188, v203
	v_sub_f32_e32 v84, v188, v204
	v_sub_f32_e32 v85, v188, v205
	v_sub_f32_e32 v86, v188, v206
	v_sub_f32_e32 v87, v188, v207
	v_sub_f32_e32 v88, v188, v208
	v_sub_f32_e32 v89, v188, v209
	v_sub_f32_e32 v90, v188, v210
	v_sub_f32_e32 v91, v188, v211
	v_sub_f32_e32 v92, v188, v212
	v_sub_f32_e32 v93, v188, v213
	v_sub_f32_e32 v94, v188, v214
	v_sub_f32_e32 v95, v188, v215
	s_nop 1
	v_mfma_f32_32x32x16_bf16 v[80:95], v[144:147], v[96:99], v[80:95]
	v_mfma_f32_32x32x16_bf16 v[80:95], v[148:151], v[100:103], v[80:95]
	v_mfma_f32_32x32x16_bf16 v[80:95], v[152:155], v[104:107], v[80:95]
	v_mfma_f32_32x32x16_bf16 v[80:95], v[156:159], v[108:111], v[80:95]
	v_sub_f32_e32 v220, v190, v200
	v_sub_f32_e32 v221, v190, v201
	v_sub_f32_e32 v222, v190, v202
	v_sub_f32_e32 v223, v190, v203
	v_sub_f32_e32 v224, v190, v204
	v_sub_f32_e32 v225, v190, v205
	v_sub_f32_e32 v226, v190, v206
	v_sub_f32_e32 v227, v190, v207
	v_sub_f32_e32 v228, v190, v208
	v_sub_f32_e32 v229, v190, v209
	v_sub_f32_e32 v230, v190, v210
	v_sub_f32_e32 v231, v190, v211
	v_sub_f32_e32 v232, v190, v212
	v_sub_f32_e32 v233, v190, v213
	v_sub_f32_e32 v234, v190, v214
	v_sub_f32_e32 v235, v190, v215
	s_nop 1
	v_mfma_f32_32x32x16_bf16 v[220:235], v[144:147], v[112:115], v[220:235]
	v_mfma_f32_32x32x16_bf16 v[220:235], v[148:151], v[116:119], v[220:235]
	v_mfma_f32_32x32x16_bf16 v[220:235], v[152:155], v[120:123], v[220:235]
	v_mfma_f32_32x32x16_bf16 v[220:235], v[156:159], v[124:127], v[220:235]
	v_exp_f32_e32 v80, v80
	v_exp_f32_e32 v81, v81
	v_exp_f32_e32 v82, v82
	v_exp_f32_e32 v83, v83
	v_exp_f32_e32 v84, v84
	v_exp_f32_e32 v85, v85
	v_exp_f32_e32 v86, v86
	v_exp_f32_e32 v87, v87
	v_exp_f32_e32 v88, v88
	v_exp_f32_e32 v89, v89
	v_exp_f32_e32 v90, v90
	v_exp_f32_e32 v91, v91
	v_exp_f32_e32 v92, v92
	v_exp_f32_e32 v93, v93
	v_exp_f32_e32 v94, v94
	v_exp_f32_e32 v95, v95
	v_exp_f32_e32 v220, v220
	v_add_f32_e32 v198, v80, v198
	v_exp_f32_e32 v221, v221
	v_add_f32_e32 v198, v81, v198
	v_exp_f32_e32 v222, v222
	v_add_f32_e32 v198, v82, v198
	v_exp_f32_e32 v223, v223
	v_add_f32_e32 v198, v83, v198
	v_exp_f32_e32 v224, v224
	v_add_f32_e32 v198, v84, v198
	v_exp_f32_e32 v225, v225
	v_add_f32_e32 v198, v85, v198
	v_exp_f32_e32 v226, v226
	v_add_f32_e32 v198, v86, v198
	v_exp_f32_e32 v227, v227
	v_add_f32_e32 v198, v87, v198
	v_exp_f32_e32 v228, v228
	v_add_f32_e32 v198, v88, v198
	v_exp_f32_e32 v229, v229
	v_add_f32_e32 v198, v89, v198
	v_exp_f32_e32 v230, v230
	v_add_f32_e32 v198, v90, v198
	v_exp_f32_e32 v231, v231
	v_add_f32_e32 v198, v91, v198
	v_exp_f32_e32 v232, v232
	v_add_f32_e32 v198, v92, v198
	v_exp_f32_e32 v233, v233
	v_add_f32_e32 v198, v93, v198
	v_exp_f32_e32 v234, v234
	v_add_f32_e32 v198, v94, v198
	v_exp_f32_e32 v235, v235
	v_add_f32_e32 v198, v95, v198
	v_cvt_pk_bf16_f32 v80, v80, v81
	v_cvt_pk_bf16_f32 v81, v82, v83
	v_cvt_pk_bf16_f32 v82, v84, v85
	v_cvt_pk_bf16_f32 v83, v86, v87
	v_cvt_pk_bf16_f32 v84, v88, v89
	v_cvt_pk_bf16_f32 v85, v90, v91
	v_cvt_pk_bf16_f32 v86, v92, v93
	v_cvt_pk_bf16_f32 v87, v94, v95
	v_mfma_f32_32x32x16_bf16 v[64:79], v[140:143], v[80:83], v[64:79]
	v_add_f32_e32 v175, v220, v175
	v_add_f32_e32 v175, v221, v175
	v_add_f32_e32 v175, v222, v175
	v_add_f32_e32 v175, v223, v175
	v_mfma_f32_32x32x16_bf16 v[48:63], v[132:135], v[80:83], v[48:63]
	v_add_f32_e32 v175, v224, v175
	v_add_f32_e32 v175, v225, v175
	v_add_f32_e32 v175, v226, v175
	v_add_f32_e32 v175, v227, v175
	v_mfma_f32_32x32x16_bf16 v[64:79], v[136:139], v[84:87], v[64:79]
	v_add_f32_e32 v175, v228, v175
	v_add_f32_e32 v175, v229, v175
	v_add_f32_e32 v175, v230, v175
	v_add_f32_e32 v175, v231, v175
	v_mfma_f32_32x32x16_bf16 v[48:63], v[128:131], v[84:87], v[48:63]
	v_add_f32_e32 v175, v232, v175
	v_add_f32_e32 v175, v233, v175
	v_add_f32_e32 v175, v234, v175
	v_add_f32_e32 v175, v235, v175
	v_cvt_pk_bf16_f32 v220, v220, v221
	v_cvt_pk_bf16_f32 v221, v222, v223
	v_cvt_pk_bf16_f32 v222, v224, v225
	v_cvt_pk_bf16_f32 v223, v226, v227
	v_cvt_pk_bf16_f32 v224, v228, v229
	v_cvt_pk_bf16_f32 v225, v230, v231
	v_cvt_pk_bf16_f32 v226, v232, v233
	v_cvt_pk_bf16_f32 v227, v234, v235
	v_mfma_f32_32x32x16_bf16 v[32:47], v[140:143], v[220:223], v[32:47]
	v_mfma_f32_32x32x16_bf16 v[16:31], v[132:135], v[220:223], v[16:31]
	v_mfma_f32_32x32x16_bf16 v[32:47], v[136:139], v[224:227], v[32:47]
	v_mfma_f32_32x32x16_bf16 v[16:31], v[128:131], v[224:227], v[16:31]
	s_branch .LBB0_340
; #define LAS __attribute__((address_space(3)))
; DI float ex2(float x) { return __builtin_amdgcn_exp2f(x); }
; template <int MODE>
; DI void sub_tile(const bf16x8 (&kf)[4], const bf16x8 (&vf)[2][2], const bf16x8 (&qf)[4], f32x16& o0, f32x16& o1, float& l, bool diag, float offs, float fm, const LAS float* fsp, int r, int h) {
;     ...
;     } else {
;         x = qk_tile(kf, qf);
; #pragma unroll
;         for (int g = 0; g < 4; ++g) {
;             const f32x4 fs = *(const LAS f32x4*)(fsp + 16 * (g >> 1) + 8 * h + 4 * (g & 1));
; #pragma unroll
;             for (int e = 0; e < 4; ++e) p[4 * g + e] = ex2(x[4 * g + e] + (fm - fs[e]));
;         }
;     }
;     if (diag) {
; #pragma unroll
;         for (int i = 0; i < 16; ++i) if (kidx(i, h) > r) p[i] = 0.f;
;     }
; template <int MODE>
; DI void attn_wg2_item(const bf16_t* Qm, const bf16_t* Km, const bf16_t* Vtm, const float* Fb, const float* KMPb, const bf16_t* G, bf16_t* Y, int bh, int qb2, int halfq, int mixer, float Mb, LAS unsigned char* lds, int tid, int wave, int lane) {
;     ...
;                 if (MODE == 2) { offA = ((nb == qblkA) || ((selA >> nb) & 1u)) ? mb2 : NEGI; offB = ((nb == qblkB) || ((selB >> nb) & 1u)) ? mb2 : NEGI; }
;                 const LAS float* fsp = (const LAS float*)(lb + AW_F) + kk * 32;
;                 if (actA) sub_tile<MODE>(kf, vf, qfA, oA0, oA1, lA, tau == qtA, offA, fmA, fsp, r, h);
.Lfox_nf1:
	s_andn2_b64 vcc, exec, s[66:67]
	s_or_b32 s66, s5, 1
	s_cbranch_vccnz .LBB0_336
	v_add_u32_e32 v179, s50, v197
	ds_read_b128 v[200:203], v179 offset:18560
	ds_read_b128 v[204:207], v179 offset:18576
	ds_read_b128 v[208:211], v179 offset:18624
	ds_read_b128 v[212:215], v179 offset:18640
	s_cmp_lg_u32 s66, s69
	s_waitcnt lgkmcnt(3)
	v_sub_f32_e32 v80, v188, v200
	v_sub_f32_e32 v81, v188, v201
	v_sub_f32_e32 v82, v188, v202
	v_sub_f32_e32 v83, v188, v203
	s_waitcnt lgkmcnt(2)
	v_sub_f32_e32 v84, v188, v204
	v_sub_f32_e32 v85, v188, v205
	v_sub_f32_e32 v86, v188, v206
	v_sub_f32_e32 v87, v188, v207
	s_waitcnt lgkmcnt(1)
	v_sub_f32_e32 v88, v188, v208
	v_sub_f32_e32 v89, v188, v209
	v_sub_f32_e32 v90, v188, v210
	v_sub_f32_e32 v91, v188, v211
	s_waitcnt lgkmcnt(0)
	v_sub_f32_e32 v92, v188, v212
	v_sub_f32_e32 v93, v188, v213
	v_sub_f32_e32 v94, v188, v214
	v_sub_f32_e32 v95, v188, v215
	s_nop 1
	v_mfma_f32_32x32x16_bf16 v[80:95], v[144:147], v[96:99], v[80:95]
	v_mfma_f32_32x32x16_bf16 v[80:95], v[148:151], v[100:103], v[80:95]
	v_mfma_f32_32x32x16_bf16 v[80:95], v[152:155], v[104:107], v[80:95]
	v_mfma_f32_32x32x16_bf16 v[80:95], v[156:159], v[108:111], v[80:95]
	s_nop 11
	v_exp_f32_e32 v15, v80
	v_exp_f32_e32 v80, v81
	v_exp_f32_e32 v81, v82
	v_exp_f32_e32 v82, v83
	v_exp_f32_e32 v83, v84
	v_exp_f32_e32 v84, v85
	v_exp_f32_e32 v85, v86
	v_exp_f32_e32 v86, v87
	v_exp_f32_e32 v87, v88
	v_exp_f32_e32 v88, v89
	v_exp_f32_e32 v89, v90
	v_exp_f32_e32 v90, v91
	v_exp_f32_e32 v91, v92
	v_exp_f32_e32 v92, v93
	v_exp_f32_e32 v93, v94
	v_exp_f32_e32 v94, v95
	s_cbranch_scc1 .LBB0_335
	v_cndmask_b32_e64 v95, v15, 0, s[14:15]
	v_cndmask_b32_e64 v15, v95, v15, s[16:17]
	v_cndmask_b32_e64 v95, v87, 0, s[30:31]
	v_cndmask_b32_e64 v80, 0, v80, s[16:17]
	v_cndmask_b32_e64 v81, v81, 0, s[18:19]
	v_cndmask_b32_e64 v82, v82, 0, s[20:21]
	v_cndmask_b32_e64 v83, v83, 0, s[22:23]
	v_cndmask_b32_e64 v84, v84, 0, s[24:25]
	v_cndmask_b32_e64 v85, v85, 0, s[26:27]
	v_cndmask_b32_e64 v86, v86, 0, s[28:29]
	v_cndmask_b32_e64 v87, v95, v87, s[34:35]
	v_cndmask_b32_e64 v88, 0, v88, s[34:35]
	v_cndmask_b32_e64 v89, v89, 0, s[36:37]
	v_cndmask_b32_e64 v90, v90, 0, s[38:39]
	v_cndmask_b32_e64 v91, v91, 0, s[40:41]
	v_cndmask_b32_e64 v92, v92, 0, s[42:43]
	v_cndmask_b32_e64 v93, v93, 0, s[44:45]
	v_cndmask_b32_e64 v94, v94, 0, s[46:47]

; #define LAS __attribute__((address_space(3)))
; DI float ex2(float x) { return __builtin_amdgcn_exp2f(x); }
; template <int MODE>
; DI void sub_tile(const bf16x8 (&kf)[4], const bf16x8 (&vf)[2][2], const bf16x8 (&qf)[4], f32x16& o0, f32x16& o1, float& l, bool diag, float offs, float fm, const LAS float* fsp, int r, int h) {
;     ...
;     } else {
;         x = qk_tile(kf, qf);
; #pragma unroll
;         for (int g = 0; g < 4; ++g) {
;             const f32x4 fs = *(const LAS f32x4*)(fsp + 16 * (g >> 1) + 8 * h + 4 * (g & 1));
; #pragma unroll
;             for (int e = 0; e < 4; ++e) p[4 * g + e] = ex2(x[4 * g + e] + (fm - fs[e]));
;         }
;     }
;     if (diag) {
; #pragma unroll
;         for (int i = 0; i < 16; ++i) if (kidx(i, h) > r) p[i] = 0.f;
;     }
; template <int MODE>
; DI void attn_wg2_item(const bf16_t* Qm, const bf16_t* Km, const bf16_t* Vtm, const float* Fb, const float* KMPb, const bf16_t* G, bf16_t* Y, int bh, int qb2, int halfq, int mixer, float Mb, LAS unsigned char* lds, int tid, int wave, int lane) {
;     ...
;                 if (actB) sub_tile<MODE>(kf, vf, qfB, oB0, oB1, lB, tau == qtB, offB, fmB, fsp, r, h);
.LBB0_336:
	s_andn2_b64 vcc, exec, s[64:65]
	s_cbranch_vccnz .LBB0_340
	v_add_u32_e32 v179, s50, v197
	ds_read_b128 v[200:203], v179 offset:18560
	ds_read_b128 v[204:207], v179 offset:18576
	ds_read_b128 v[208:211], v179 offset:18624
	ds_read_b128 v[212:215], v179 offset:18640
	s_cmp_lg_u32 s66, s84
	s_waitcnt lgkmcnt(3)
	v_sub_f32_e32 v80, v190, v200
	v_sub_f32_e32 v81, v190, v201
	v_sub_f32_e32 v82, v190, v202
	v_sub_f32_e32 v83, v190, v203
	s_waitcnt lgkmcnt(2)
	v_sub_f32_e32 v84, v190, v204
	v_sub_f32_e32 v85, v190, v205
	v_sub_f32_e32 v86, v190, v206
	v_sub_f32_e32 v87, v190, v207
	s_waitcnt lgkmcnt(1)
	v_sub_f32_e32 v88, v190, v208
	v_sub_f32_e32 v89, v190, v209
	v_sub_f32_e32 v90, v190, v210
	v_sub_f32_e32 v91, v190, v211
	s_waitcnt lgkmcnt(0)
	v_sub_f32_e32 v92, v190, v212
	v_sub_f32_e32 v93, v190, v213
	v_sub_f32_e32 v94, v190, v214
	v_sub_f32_e32 v95, v190, v215
	s_nop 1
	v_mfma_f32_32x32x16_bf16 v[80:95], v[144:147], v[112:115], v[80:95]
	v_mfma_f32_32x32x16_bf16 v[80:95], v[148:151], v[116:119], v[80:95]
	v_mfma_f32_32x32x16_bf16 v[80:95], v[152:155], v[120:123], v[80:95]
	v_mfma_f32_32x32x16_bf16 v[80:95], v[156:159], v[124:127], v[80:95]
	s_nop 11
	v_exp_f32_e32 v15, v80
	v_exp_f32_e32 v80, v81
	v_exp_f32_e32 v81, v82
	v_exp_f32_e32 v82, v83
	v_exp_f32_e32 v83, v84
	v_exp_f32_e32 v84, v85
	v_exp_f32_e32 v85, v86
	v_exp_f32_e32 v86, v87
	v_exp_f32_e32 v87, v88
	v_exp_f32_e32 v88, v89
	v_exp_f32_e32 v89, v90
	v_exp_f32_e32 v90, v91
	v_exp_f32_e32 v91, v92
	v_exp_f32_e32 v92, v93
	v_exp_f32_e32 v93, v94
	v_exp_f32_e32 v94, v95
	s_cbranch_scc1 .LBB0_339
	v_cndmask_b32_e64 v95, v15, 0, s[14:15]
	v_cndmask_b32_e64 v15, v95, v15, s[16:17]
	v_cndmask_b32_e64 v95, v87, 0, s[30:31]
	v_cndmask_b32_e64 v80, 0, v80, s[16:17]
	v_cndmask_b32_e64 v81, v81, 0, s[18:19]
	v_cndmask_b32_e64 v82, v82, 0, s[20:21]
	v_cndmask_b32_e64 v83, v83, 0, s[22:23]
	v_cndmask_b32_e64 v84, v84, 0, s[24:25]
	v_cndmask_b32_e64 v85, v85, 0, s[26:27]
	v_cndmask_b32_e64 v86, v86, 0, s[28:29]
	v_cndmask_b32_e64 v87, v95, v87, s[34:35]
	v_cndmask_b32_e64 v88, 0, v88, s[34:35]
	v_cndmask_b32_e64 v89, v89, 0, s[36:37]
	v_cndmask_b32_e64 v90, v90, 0, s[38:39]
	v_cndmask_b32_e64 v91, v91, 0, s[40:41]
	v_cndmask_b32_e64 v92, v92, 0, s[42:43]
	v_cndmask_b32_e64 v93, v93, 0, s[44:45]
	v_cndmask_b32_e64 v94, v94, 0, s[46:47]

; template <int MODE>
; DI void sub_tile(const bf16x8 (&kf)[4], const bf16x8 (&vf)[2][2], const bf16x8 (&qf)[4], f32x16& o0, f32x16& o1, float& l, bool diag, float offs, float fm, const LAS float* fsp, int r, int h) {
;     f32x16 x;
;     float p[16];
;     if (MODE == 2) {
; #pragma unroll
;         for (int i = 0; i < 16; ++i) x[i] = offs;
; #pragma unroll
;         for (int sp = 0; sp < 4; ++sp) x = mfma32(kf[sp], qf[sp], x);
; #pragma unroll
;         for (int i = 0; i < 16; ++i) p[i] = ex2(x[i]);
;     } else {
;         x = qk_tile(kf, qf);
; #pragma unroll
;         for (int g = 0; g < 4; ++g) {
;             const f32x4 fs = *(const LAS f32x4*)(fsp + 16 * (g >> 1) + 8 * h + 4 * (g & 1));
; #pragma unroll
;             for (int e = 0; e < 4; ++e) p[4 * g + e] = ex2(x[4 * g + e] + (fm - fs[e]));
;         }
;     }
;     if (diag) {
; #pragma unroll
;         for (int i = 0; i < 16; ++i) if (kidx(i, h) > r) p[i] = 0.f;
;     }
; #pragma unroll
; template <int MODE>
; DI void attn_wg2_item(const bf16_t* Qm, const bf16_t* Km, const bf16_t* Vtm, const float* Fb, const float* KMPb, const bf16_t* G, bf16_t* Y, int bh, int qb2, int halfq, int mixer, float Mb, LAS unsigned char* lds, int tid, int wave, int lane) {
;     ...
;             const int tau = cur * 2 + kk, nb = tau >> 3;
;             bool actA = tau <= qtA, actB = tau <= qtB;
;             if (MODE == 2) { actA = actA && ((visA >> nb) & 1u); actB = actB && ((visB >> nb) & 1u); }
;             if (actA || actB) {
;                 bf16x8 kf[4], vf[2][2];
; #pragma unroll
;                 for (int sp = 0; sp < 4; ++sp) kf[sp] = *(LAS bf16x8*)(lb + kra + kk * 32 * 144 + sp * 32);
; #pragma unroll
;                 for (int dd = 0; dd < 2; ++dd)
; #pragma unroll
;                     for (int s = 0; s < 2; ++s) vf[dd][s] = *(LAS bf16x8*)(lb + vra + dd * 32 * 144 + kk * 64 + s * 32);
;                 float offA = mb2, offB = mb2;
;                 if (MODE == 2) { offA = ((nb == qblkA) || ((selA >> nb) & 1u)) ? mb2 : NEGI; offB = ((nb == qblkB) || ((selB >> nb) & 1u)) ? mb2 : NEGI; }
;                 const LAS float* fsp = (const LAS float*)(lb + AW_F) + kk * 32;
;                 if (actA) sub_tile<MODE>(kf, vf, qfA, oA0, oA1, lA, tau == qtA, offA, fmA, fsp, r, h);
;                 if (actB) sub_tile<MODE>(kf, vf, qfB, oB0, oB1, lB, tau == qtB, offB, fmB, fsp, r, h);
.LBB0_340:
	s_cmp_le_i32 s5, s69
	s_cselect_b64 s[66:67], -1, 0
	s_cmp_le_i32 s5, s84
	s_cselect_b64 s[64:65], -1, 0
	s_or_b64 s[78:79], s[66:67], s[64:65]
	s_andn2_b64 vcc, exec, s[78:79]
	s_cbranch_vccnz .LBB0_349
	s_waitcnt lgkmcnt(4)
	ds_read_b128 v[156:159], v14
	ds_read_b128 v[144:147], v14 offset:32
	ds_read_b128 v[148:151], v14 offset:64
	ds_read_b128 v[152:155], v14 offset:96
	s_waitcnt lgkmcnt(7)
	ds_read_b128 v[140:143], v0 offset:9216
	s_waitcnt lgkmcnt(7)
	ds_read_b128 v[136:139], v0 offset:9248
	s_waitcnt lgkmcnt(7)
	ds_read_b128 v[132:135], v0 offset:13824
	s_waitcnt lgkmcnt(7)
	ds_read_b128 v[128:131], v0 offset:13856
	s_and_b64 s[78:79], s[66:67], s[64:65]
	s_cbranch_scc0 .Lfox_nf0
	s_cmp_eq_u32 s5, s69
	s_cbranch_scc1 .Lfox_nf0
	s_cmp_eq_u32 s5, s84
	s_cbranch_scc1 .Lfox_nf0
	v_add_u32_e32 v0, s50, v197
	ds_read_b128 v[200:203], v0 offset:18432
	ds_read_b128 v[204:207], v0 offset:18448
	ds_read_b128 v[208:211], v0 offset:18496
	ds_read_b128 v[212:215], v0 offset:18512
	s_waitcnt lgkmcnt(0)
	v_sub_f32_e32 v80, v188, v200
	v_sub_f32_e32 v81, v188, v201
	v_sub_f32_e32 v82, v188, v202
	v_sub_f32_e32 v83, v188, v203
	v_sub_f32_e32 v84, v188, v204
	v_sub_f32_e32 v85, v188, v205
	v_sub_f32_e32 v86, v188, v206
	v_sub_f32_e32 v87, v188, v207
	v_sub_f32_e32 v88, v188, v208
	v_sub_f32_e32 v89, v188, v209
	v_sub_f32_e32 v90, v188, v210
	v_sub_f32_e32 v91, v188, v211
	v_sub_f32_e32 v92, v188, v212
	v_sub_f32_e32 v93, v188, v213
	v_sub_f32_e32 v94, v188, v214
	v_sub_f32_e32 v95, v188, v215
	s_nop 1
	v_mfma_f32_32x32x16_bf16 v[80:95], v[156:159], v[96:99], v[80:95]
	v_mfma_f32_32x32x16_bf16 v[80:95], v[144:147], v[100:103], v[80:95]
	v_mfma_f32_32x32x16_bf16 v[80:95], v[148:151], v[104:107], v[80:95]
	v_mfma_f32_32x32x16_bf16 v[80:95], v[152:155], v[108:111], v[80:95]
	v_sub_f32_e32 v220, v190, v200
	v_sub_f32_e32 v221, v190, v201
	v_sub_f32_e32 v222, v190, v202
	v_sub_f32_e32 v223, v190, v203
	v_sub_f32_e32 v224, v190, v204
	v_sub_f32_e32 v225, v190, v205
	v_sub_f32_e32 v226, v190, v206
	v_sub_f32_e32 v227, v190, v207
	v_sub_f32_e32 v228, v190, v208
	v_sub_f32_e32 v229, v190, v209
	v_sub_f32_e32 v230, v190, v210
	v_sub_f32_e32 v231, v190, v211
	v_sub_f32_e32 v232, v190, v212
	v_sub_f32_e32 v233, v190, v213
	v_sub_f32_e32 v234, v190, v214
	v_sub_f32_e32 v235, v190, v215
	s_nop 1
	v_mfma_f32_32x32x16_bf16 v[220:235], v[156:159], v[112:115], v[220:235]
	v_mfma_f32_32x32x16_bf16 v[220:235], v[144:147], v[116:119], v[220:235]
	v_mfma_f32_32x32x16_bf16 v[220:235], v[148:151], v[120:123], v[220:235]
	v_mfma_f32_32x32x16_bf16 v[220:235], v[152:155], v[124:127], v[220:235]
	v_exp_f32_e32 v80, v80
	v_exp_f32_e32 v81, v81
	v_exp_f32_e32 v82, v82
	v_exp_f32_e32 v83, v83
	v_exp_f32_e32 v84, v84
	v_exp_f32_e32 v85, v85
	v_exp_f32_e32 v86, v86
	v_exp_f32_e32 v87, v87
	v_exp_f32_e32 v88, v88
	v_exp_f32_e32 v89, v89
	v_exp_f32_e32 v90, v90
	v_exp_f32_e32 v91, v91
	v_exp_f32_e32 v92, v92
	v_exp_f32_e32 v93, v93
	v_exp_f32_e32 v94, v94
	v_exp_f32_e32 v95, v95
	v_exp_f32_e32 v220, v220
	v_add_f32_e32 v198, v80, v198
	v_exp_f32_e32 v221, v221
	v_add_f32_e32 v198, v81, v198
	v_exp_f32_e32 v222, v222
	v_add_f32_e32 v198, v82, v198
	v_exp_f32_e32 v223, v223
	v_add_f32_e32 v198, v83, v198
	v_exp_f32_e32 v224, v224
	v_add_f32_e32 v198, v84, v198
	v_exp_f32_e32 v225, v225
	v_add_f32_e32 v198, v85, v198
	v_exp_f32_e32 v226, v226
	v_add_f32_e32 v198, v86, v198
	v_exp_f32_e32 v227, v227
	v_add_f32_e32 v198, v87, v198
	v_exp_f32_e32 v228, v228
	v_add_f32_e32 v198, v88, v198
	v_exp_f32_e32 v229, v229
	v_add_f32_e32 v198, v89, v198
	v_exp_f32_e32 v230, v230
	v_add_f32_e32 v198, v90, v198
	v_exp_f32_e32 v231, v231
	v_add_f32_e32 v198, v91, v198
	v_exp_f32_e32 v232, v232
	v_add_f32_e32 v198, v92, v198
	v_exp_f32_e32 v233, v233
	v_add_f32_e32 v198, v93, v198
	v_exp_f32_e32 v234, v234
	v_add_f32_e32 v198, v94, v198
	v_exp_f32_e32 v235, v235
	v_add_f32_e32 v198, v95, v198
	v_cvt_pk_bf16_f32 v80, v80, v81
	v_cvt_pk_bf16_f32 v81, v82, v83
	v_cvt_pk_bf16_f32 v82, v84, v85
	v_cvt_pk_bf16_f32 v83, v86, v87
	v_cvt_pk_bf16_f32 v84, v88, v89
	v_cvt_pk_bf16_f32 v85, v90, v91
	v_cvt_pk_bf16_f32 v86, v92, v93
	v_cvt_pk_bf16_f32 v87, v94, v95
	v_mfma_f32_32x32x16_bf16 v[64:79], v[140:143], v[80:83], v[64:79]
	v_add_f32_e32 v175, v220, v175
	v_add_f32_e32 v175, v221, v175
	v_add_f32_e32 v175, v222, v175
	v_add_f32_e32 v175, v223, v175
	v_mfma_f32_32x32x16_bf16 v[48:63], v[132:135], v[80:83], v[48:63]
	v_add_f32_e32 v175, v224, v175
	v_add_f32_e32 v175, v225, v175
	v_add_f32_e32 v175, v226, v175
	v_add_f32_e32 v175, v227, v175
	v_mfma_f32_32x32x16_bf16 v[64:79], v[136:139], v[84:87], v[64:79]
	v_add_f32_e32 v175, v228, v175
	v_add_f32_e32 v175, v229, v175
	v_add_f32_e32 v175, v230, v175
	v_add_f32_e32 v175, v231, v175
	v_mfma_f32_32x32x16_bf16 v[48:63], v[128:131], v[84:87], v[48:63]
	v_add_f32_e32 v175, v232, v175
	v_add_f32_e32 v175, v233, v175
	v_add_f32_e32 v175, v234, v175
	v_add_f32_e32 v175, v235, v175
	v_cvt_pk_bf16_f32 v220, v220, v221
	v_cvt_pk_bf16_f32 v221, v222, v223
	v_cvt_pk_bf16_f32 v222, v224, v225
	v_cvt_pk_bf16_f32 v223, v226, v227
	v_cvt_pk_bf16_f32 v224, v228, v229
	v_cvt_pk_bf16_f32 v225, v230, v231
	v_cvt_pk_bf16_f32 v226, v232, v233
	v_cvt_pk_bf16_f32 v227, v234, v235
	v_mfma_f32_32x32x16_bf16 v[32:47], v[140:143], v[220:223], v[32:47]
	v_mfma_f32_32x32x16_bf16 v[16:31], v[132:135], v[220:223], v[16:31]
	v_mfma_f32_32x32x16_bf16 v[32:47], v[136:139], v[224:227], v[32:47]
	v_mfma_f32_32x32x16_bf16 v[16:31], v[128:131], v[224:227], v[16:31]
	s_branch .LBB0_349
; #define LAS __attribute__((address_space(3)))
; DI float ex2(float x) { return __builtin_amdgcn_exp2f(x); }
; template <int MODE>
; DI void sub_tile(const bf16x8 (&kf)[4], const bf16x8 (&vf)[2][2], const bf16x8 (&qf)[4], f32x16& o0, f32x16& o1, float& l, bool diag, float offs, float fm, const LAS float* fsp, int r, int h) {
;     ...
;     } else {
;         x = qk_tile(kf, qf);
; #pragma unroll
;         for (int g = 0; g < 4; ++g) {
;             const f32x4 fs = *(const LAS f32x4*)(fsp + 16 * (g >> 1) + 8 * h + 4 * (g & 1));
; #pragma unroll
;             for (int e = 0; e < 4; ++e) p[4 * g + e] = ex2(x[4 * g + e] + (fm - fs[e]));
;         }
;     }
;     if (diag) {
; #pragma unroll
;         for (int i = 0; i < 16; ++i) if (kidx(i, h) > r) p[i] = 0.f;
;     }
; template <int MODE>
; DI void attn_wg2_item(const bf16_t* Qm, const bf16_t* Km, const bf16_t* Vtm, const float* Fb, const float* KMPb, const bf16_t* G, bf16_t* Y, int bh, int qb2, int halfq, int mixer, float Mb, LAS unsigned char* lds, int tid, int wave, int lane) {
;     ...
;                 if (MODE == 2) { offA = ((nb == qblkA) || ((selA >> nb) & 1u)) ? mb2 : NEGI; offB = ((nb == qblkB) || ((selB >> nb) & 1u)) ? mb2 : NEGI; }
;                 const LAS float* fsp = (const LAS float*)(lb + AW_F) + kk * 32;
;                 if (actA) sub_tile<MODE>(kf, vf, qfA, oA0, oA1, lA, tau == qtA, offA, fmA, fsp, r, h);
.Lfox_nf0:
	s_andn2_b64 vcc, exec, s[66:67]
	v_add_u32_e32 v0, s50, v197
	s_cbranch_vccnz .LBB0_345
	ds_read_b128 v[200:203], v0 offset:18432
	ds_read_b128 v[204:207], v0 offset:18448
	ds_read_b128 v[208:211], v0 offset:18496
	ds_read_b128 v[212:215], v0 offset:18512
	s_cmp_lg_u32 s5, s69
	s_waitcnt lgkmcnt(3)
	v_sub_f32_e32 v80, v188, v200
	v_sub_f32_e32 v81, v188, v201
	v_sub_f32_e32 v82, v188, v202
	v_sub_f32_e32 v83, v188, v203
	s_waitcnt lgkmcnt(2)
	v_sub_f32_e32 v84, v188, v204
	v_sub_f32_e32 v85, v188, v205
	v_sub_f32_e32 v86, v188, v206
	v_sub_f32_e32 v87, v188, v207
	s_waitcnt lgkmcnt(1)
	v_sub_f32_e32 v88, v188, v208
	v_sub_f32_e32 v89, v188, v209
	v_sub_f32_e32 v90, v188, v210
	v_sub_f32_e32 v91, v188, v211
	s_waitcnt lgkmcnt(0)
	v_sub_f32_e32 v92, v188, v212
	v_sub_f32_e32 v93, v188, v213
	v_sub_f32_e32 v94, v188, v214
	v_sub_f32_e32 v95, v188, v215
	s_nop 1
	v_mfma_f32_32x32x16_bf16 v[80:95], v[156:159], v[96:99], v[80:95]
	v_mfma_f32_32x32x16_bf16 v[80:95], v[144:147], v[100:103], v[80:95]
	v_mfma_f32_32x32x16_bf16 v[80:95], v[148:151], v[104:107], v[80:95]
	v_mfma_f32_32x32x16_bf16 v[80:95], v[152:155], v[108:111], v[80:95]
	s_nop 11
	v_exp_f32_e32 v14, v80
	v_exp_f32_e32 v15, v81
	v_exp_f32_e32 v80, v82
	v_exp_f32_e32 v81, v83
	v_exp_f32_e32 v82, v84
	v_exp_f32_e32 v83, v85
	v_exp_f32_e32 v84, v86
	v_exp_f32_e32 v85, v87
	v_exp_f32_e32 v86, v88
	v_exp_f32_e32 v87, v89
	v_exp_f32_e32 v88, v90
	v_exp_f32_e32 v89, v91
	v_exp_f32_e32 v90, v92
	v_exp_f32_e32 v91, v93
	v_exp_f32_e32 v92, v94
	v_exp_f32_e32 v93, v95
	s_cbranch_scc1 .LBB0_344
	v_cndmask_b32_e64 v94, v14, 0, s[14:15]
	v_cndmask_b32_e64 v14, v94, v14, s[16:17]
	v_cndmask_b32_e64 v94, v86, 0, s[30:31]
	v_cndmask_b32_e64 v15, 0, v15, s[16:17]
	v_cndmask_b32_e64 v80, v80, 0, s[18:19]
	v_cndmask_b32_e64 v81, v81, 0, s[20:21]
	v_cndmask_b32_e64 v82, v82, 0, s[22:23]
	v_cndmask_b32_e64 v83, v83, 0, s[24:25]
	v_cndmask_b32_e64 v84, v84, 0, s[26:27]
	v_cndmask_b32_e64 v85, v85, 0, s[28:29]
	v_cndmask_b32_e64 v86, v94, v86, s[34:35]
	v_cndmask_b32_e64 v87, 0, v87, s[34:35]
	v_cndmask_b32_e64 v88, v88, 0, s[36:37]
	v_cndmask_b32_e64 v89, v89, 0, s[38:39]
	v_cndmask_b32_e64 v90, v90, 0, s[40:41]
	v_cndmask_b32_e64 v91, v91, 0, s[42:43]
	v_cndmask_b32_e64 v92, v92, 0, s[44:45]
	v_cndmask_b32_e64 v93, v93, 0, s[46:47]

; #define LAS __attribute__((address_space(3)))
; DI float ex2(float x) { return __builtin_amdgcn_exp2f(x); }
; template <int MODE>
; DI void sub_tile(const bf16x8 (&kf)[4], const bf16x8 (&vf)[2][2], const bf16x8 (&qf)[4], f32x16& o0, f32x16& o1, float& l, bool diag, float offs, float fm, const LAS float* fsp, int r, int h) {
;     ...
;     } else {
;         x = qk_tile(kf, qf);
; #pragma unroll
;         for (int g = 0; g < 4; ++g) {
;             const f32x4 fs = *(const LAS f32x4*)(fsp + 16 * (g >> 1) + 8 * h + 4 * (g & 1));
; #pragma unroll
;             for (int e = 0; e < 4; ++e) p[4 * g + e] = ex2(x[4 * g + e] + (fm - fs[e]));
;         }
;     }
;     if (diag) {
; #pragma unroll
;         for (int i = 0; i < 16; ++i) if (kidx(i, h) > r) p[i] = 0.f;
;     }
; template <int MODE>
; DI void attn_wg2_item(const bf16_t* Qm, const bf16_t* Km, const bf16_t* Vtm, const float* Fb, const float* KMPb, const bf16_t* G, bf16_t* Y, int bh, int qb2, int halfq, int mixer, float Mb, LAS unsigned char* lds, int tid, int wave, int lane) {
;     ...
;                 if (actB) sub_tile<MODE>(kf, vf, qfB, oB0, oB1, lB, tau == qtB, offB, fmB, fsp, r, h);
.LBB0_345:
	s_andn2_b64 vcc, exec, s[64:65]
	s_cbranch_vccnz .LBB0_349
	ds_read_b128 v[200:203], v0 offset:18432
	ds_read_b128 v[204:207], v0 offset:18448
	ds_read_b128 v[208:211], v0 offset:18496
	ds_read_b128 v[212:215], v0 offset:18512
	s_cmp_lg_u32 s5, s84
	s_waitcnt lgkmcnt(3)
	v_sub_f32_e32 v80, v190, v200
	v_sub_f32_e32 v81, v190, v201
	v_sub_f32_e32 v82, v190, v202
	v_sub_f32_e32 v83, v190, v203
	s_waitcnt lgkmcnt(2)
	v_sub_f32_e32 v84, v190, v204
	v_sub_f32_e32 v85, v190, v205
	v_sub_f32_e32 v86, v190, v206
	v_sub_f32_e32 v87, v190, v207
	s_waitcnt lgkmcnt(1)
	v_sub_f32_e32 v88, v190, v208
	v_sub_f32_e32 v89, v190, v209
	v_sub_f32_e32 v90, v190, v210
	v_sub_f32_e32 v91, v190, v211
	s_waitcnt lgkmcnt(0)
	v_sub_f32_e32 v92, v190, v212
	v_sub_f32_e32 v93, v190, v213
	v_sub_f32_e32 v94, v190, v214
	v_sub_f32_e32 v95, v190, v215
	s_nop 1
	v_mfma_f32_32x32x16_bf16 v[80:95], v[156:159], v[112:115], v[80:95]
	v_mfma_f32_32x32x16_bf16 v[80:95], v[144:147], v[116:119], v[80:95]
	v_mfma_f32_32x32x16_bf16 v[80:95], v[148:151], v[120:123], v[80:95]
	v_mfma_f32_32x32x16_bf16 v[80:95], v[152:155], v[124:127], v[80:95]
	s_nop 11
	v_exp_f32_e32 v14, v80
	v_exp_f32_e32 v15, v81
	v_exp_f32_e32 v80, v82
	v_exp_f32_e32 v81, v83
	v_exp_f32_e32 v82, v84
	v_exp_f32_e32 v83, v85
	v_exp_f32_e32 v84, v86
	v_exp_f32_e32 v85, v87
	v_exp_f32_e32 v86, v88
	v_exp_f32_e32 v87, v89
	v_exp_f32_e32 v88, v90
	v_exp_f32_e32 v89, v91
	v_exp_f32_e32 v0, v92
	v_exp_f32_e32 v90, v93
	v_exp_f32_e32 v91, v94
	v_exp_f32_e32 v92, v95
	s_cbranch_scc1 .LBB0_348
	v_cndmask_b32_e64 v93, v14, 0, s[14:15]
	v_cndmask_b32_e64 v14, v93, v14, s[16:17]
	v_cndmask_b32_e64 v93, v86, 0, s[30:31]
	v_cndmask_b32_e64 v15, 0, v15, s[16:17]
	v_cndmask_b32_e64 v80, v80, 0, s[18:19]
	v_cndmask_b32_e64 v81, v81, 0, s[20:21]
	v_cndmask_b32_e64 v82, v82, 0, s[22:23]
	v_cndmask_b32_e64 v83, v83, 0, s[24:25]
	v_cndmask_b32_e64 v84, v84, 0, s[26:27]
	v_cndmask_b32_e64 v85, v85, 0, s[28:29]
	v_cndmask_b32_e64 v86, v93, v86, s[34:35]
	v_cndmask_b32_e64 v87, 0, v87, s[34:35]
	v_cndmask_b32_e64 v88, v88, 0, s[36:37]
	v_cndmask_b32_e64 v89, v89, 0, s[38:39]
	v_cndmask_b32_e64 v0, v0, 0, s[40:41]
	v_cndmask_b32_e64 v90, v90, 0, s[42:43]
	v_cndmask_b32_e64 v91, v91, 0, s[44:45]
	v_cndmask_b32_e64 v92, v92, 0, s[46:47]

; #define LAS __attribute__((address_space(3)))
; template <int MODE>
; DI void attn_wg2_item(const bf16_t* Qm, const bf16_t* Km, const bf16_t* Vtm, const float* Fb, const float* KMPb, const bf16_t* G, bf16_t* Y, int bh, int qb2, int halfq, int mixer, float Mb, LAS unsigned char* lds, int tid, int wave, int lane) {
;     ...
;         if (nxt >= 0) {
;             LAS unsigned char* nb_ = lds + (buf ^ 1) * AW_BUF;
;             *(LAS bf16x8*)(nb_ + kws) = kreg;
;             *(LAS u32x4*)(nb_ + vws) = vreg;
;             if (MODE == 3 && tid < 16) *(LAS f32x4*)(nb_ + AW_F + tid * 16) = freg * LOG2E;
;         }
;         __syncthreads();
;         buf ^= 1; cur = nxt;
.LBB0_349:
	s_andn2_b64 vcc, exec, s[62:63]
	s_xor_b32 s85, s85, 1
	s_cbranch_vccnz .LBB0_353
	s_mul_i32 s5, s85, 0x4900
	s_add_i32 s5, s5, 0
	v_add_u32_e32 v0, s5, v174
	s_waitcnt vmcnt(1)
	ds_write_b128 v0, v[6:9]
	s_waitcnt vmcnt(0)
	ds_write_b128 v0, v[10:13] offset:9216
	s_and_saveexec_b64 s[62:63], s[12:13]
	v_add_u32_e32 v0, s5, v186
	v_mul_f32_e32 v2, 0x3fb8aa3b, v2
	v_mul_f32_e32 v3, 0x3fb8aa3b, v3
	v_mul_f32_e32 v4, 0x3fb8aa3b, v4
	v_mul_f32_e32 v5, 0x3fb8aa3b, v5
	ds_write_b128 v0, v[2:5] offset:18432
	s_or_b64 exec, exec, s[62:63]

; #define LAS __attribute__((address_space(3)))
; DI f32x16 mfma32(bf16x8 a, bf16x8 b, f32x16 c) { return __builtin_amdgcn_mfma_f32_32x32x16_bf16(a, b, c, 0, 0, 0); }
; template <int MODE>
; DI void sub_tile(const bf16x8 (&kf)[4], const bf16x8 (&vf)[2][2], const bf16x8 (&qf)[4], f32x16& o0, f32x16& o1, float& l, bool diag, float offs, float fm, const LAS float* fsp, int r, int h) {
;     ...
;     if (MODE == 2) {
; #pragma unroll
;         for (int i = 0; i < 16; ++i) x[i] = offs;
; #pragma unroll
;         for (int sp = 0; sp < 4; ++sp) x = mfma32(kf[sp], qf[sp], x);
; template <int MODE>
; DI void attn_wg2_item(const bf16_t* Qm, const bf16_t* Km, const bf16_t* Vtm, const float* Fb, const float* KMPb, const bf16_t* G, bf16_t* Y, int bh, int qb2, int halfq, int mixer, float Mb, LAS unsigned char* lds, int tid, int wave, int lane) {
;     ...
;             const int tau = cur * 2 + kk, nb = tau >> 3;
;             bool actA = tau <= qtA, actB = tau <= qtB;
;             if (MODE == 2) { actA = actA && ((visA >> nb) & 1u); actB = actB && ((visB >> nb) & 1u); }
;             if (actA || actB) {
;                 bf16x8 kf[4], vf[2][2];
; #pragma unroll
;                 for (int sp = 0; sp < 4; ++sp) kf[sp] = *(LAS bf16x8*)(lb + kra + kk * 32 * 144 + sp * 32);
; #pragma unroll
;                 for (int dd = 0; dd < 2; ++dd)
; #pragma unroll
;                     for (int s = 0; s < 2; ++s) vf[dd][s] = *(LAS bf16x8*)(lb + vra + dd * 32 * 144 + kk * 64 + s * 32);
;                 float offA = mb2, offB = mb2;
;                 if (MODE == 2) { offA = ((nb == qblkA) || ((selA >> nb) & 1u)) ? mb2 : NEGI; offB = ((nb == qblkB) || ((selB >> nb) & 1u)) ? mb2 : NEGI; }
.LBB0_390:
	s_and_b32 s47, s46, 3
	s_cmp_lg_u32 s47, 3
	s_cbranch_scc1 .Lmoba_keep_offs
	s_lshr_b32 s47, s46, 2
	s_lshl_b32 s48, 1, s47
	s_cmp_eq_u32 s47, s86
	s_cselect_b64 s[92:93], -1, 0
	v_and_b32_e32 v196, s48, v163
	v_and_b32_e32 v212, s48, v171
	v_cmp_ne_u32_e32 vcc, 0, v196
	s_or_b64 vcc, vcc, s[92:93]
	s_cmp_eq_u32 s47, s78
	s_cselect_b64 s[92:93], -1, 0
	v_cndmask_b32_e32 v196, v195, v184, vcc
	v_cmp_ne_u32_e32 vcc, 0, v212
	s_or_b64 vcc, vcc, s[92:93]
	v_mov_b32_e32 v197, v196
	v_mov_b32_e32 v198, v196
	v_mov_b32_e32 v199, v196
	v_mov_b32_e32 v200, v196
	v_mov_b32_e32 v201, v196
	v_mov_b32_e32 v202, v196
	v_mov_b32_e32 v203, v196
	v_mov_b32_e32 v204, v196
	v_mov_b32_e32 v205, v196
	v_mov_b32_e32 v206, v196
	v_mov_b32_e32 v207, v196
	v_mov_b32_e32 v208, v196
	v_mov_b32_e32 v209, v196
	v_mov_b32_e32 v210, v196
	v_mov_b32_e32 v211, v196
	v_cndmask_b32_e32 v212, v195, v184, vcc
	v_mov_b32_e32 v213, v212
	v_mov_b32_e32 v214, v212
	v_mov_b32_e32 v215, v212
	v_mov_b32_e32 v216, v212
	v_mov_b32_e32 v217, v212
	v_mov_b32_e32 v218, v212
	v_mov_b32_e32 v219, v212
	v_mov_b32_e32 v220, v212
	v_mov_b32_e32 v221, v212
	v_mov_b32_e32 v222, v212
	v_mov_b32_e32 v223, v212
	v_mov_b32_e32 v224, v212
	v_mov_b32_e32 v225, v212
	v_mov_b32_e32 v226, v212
	v_mov_b32_e32 v227, v212

; template <int MODE>
; DI void sub_tile(const bf16x8 (&kf)[4], const bf16x8 (&vf)[2][2], const bf16x8 (&qf)[4], f32x16& o0, f32x16& o1, float& l, bool diag, float offs, float fm, const LAS float* fsp, int r, int h) {
;     f32x16 x;
;     float p[16];
;     if (MODE == 2) {
; #pragma unroll
;         for (int i = 0; i < 16; ++i) x[i] = offs;
; #pragma unroll
;         for (int sp = 0; sp < 4; ++sp) x = mfma32(kf[sp], qf[sp], x);
; #pragma unroll
;         for (int i = 0; i < 16; ++i) p[i] = ex2(x[i]);
;     } else {
;         x = qk_tile(kf, qf);
; #pragma unroll
;         for (int g = 0; g < 4; ++g) {
;             const f32x4 fs = *(const LAS f32x4*)(fsp + 16 * (g >> 1) + 8 * h + 4 * (g & 1));
; #pragma unroll
;             for (int e = 0; e < 4; ++e) p[4 * g + e] = ex2(x[4 * g + e] + (fm - fs[e]));
;         }
;     }
;     if (diag) {
; #pragma unroll
;         for (int i = 0; i < 16; ++i) if (kidx(i, h) > r) p[i] = 0.f;
;     }
; #pragma unroll
; template <int MODE>
; DI void attn_wg2_item(const bf16_t* Qm, const bf16_t* Km, const bf16_t* Vtm, const float* Fb, const float* KMPb, const bf16_t* G, bf16_t* Y, int bh, int qb2, int halfq, int mixer, float Mb, LAS unsigned char* lds, int tid, int wave, int lane) {
;     ...
;             const int tau = cur * 2 + kk, nb = tau >> 3;
;             bool actA = tau <= qtA, actB = tau <= qtB;
;             if (MODE == 2) { actA = actA && ((visA >> nb) & 1u); actB = actB && ((visB >> nb) & 1u); }
;             if (actA || actB) {
;                 bf16x8 kf[4], vf[2][2];
; #pragma unroll
;                 for (int sp = 0; sp < 4; ++sp) kf[sp] = *(LAS bf16x8*)(lb + kra + kk * 32 * 144 + sp * 32);
; #pragma unroll
;                 for (int dd = 0; dd < 2; ++dd)
; #pragma unroll
;                     for (int s = 0; s < 2; ++s) vf[dd][s] = *(LAS bf16x8*)(lb + vra + dd * 32 * 144 + kk * 64 + s * 32);
;                 float offA = mb2, offB = mb2;
;                 if (MODE == 2) { offA = ((nb == qblkA) || ((selA >> nb) & 1u)) ? mb2 : NEGI; offB = ((nb == qblkB) || ((selB >> nb) & 1u)) ? mb2 : NEGI; }
;                 const LAS float* fsp = (const LAS float*)(lb + AW_F) + kk * 32;
;                 if (actA) sub_tile<MODE>(kf, vf, qfA, oA0, oA1, lA, tau == qtA, offA, fmA, fsp, r, h);
;                 if (actB) sub_tile<MODE>(kf, vf, qfB, oB0, oB1, lB, tau == qtB, offB, fmB, fsp, r, h);
.LBB0_393:
	s_mul_i32 s47, s79, 0x4900
	s_add_i32 s47, s47, 0
	s_lshl_b32 s87, s46, 1
	s_lshr_b32 s88, s46, 2
	s_cmp_lt_i32 s87, s84
	v_add_u32_e32 v0, s47, v175
	v_add_u32_e32 v10, s47, v173
	s_cselect_b64 s[46:47], -1, 0
	s_cmp_lt_i32 s87, s85
	s_cselect_b64 s[64:65], -1, 0
	s_lshl_b32 s89, 1, s88
	v_and_b32_e32 v11, s89, v176
	v_cmp_ne_u32_e32 vcc, 0, v11
	v_and_b32_e32 v11, s89, v177
	s_and_b64 s[48:49], s[46:47], vcc
	v_cmp_ne_u32_e64 s[46:47], 0, v11
	s_and_b64 s[66:67], s[64:65], s[46:47]
	s_or_b64 s[68:69], s[48:49], s[66:67]
	v_add_u32_e32 v14, v0, v172
	v_add_u32_e32 v0, v10, v172
	s_and_saveexec_b64 s[64:65], s[68:69]
	s_cbranch_execz .LBB0_403
	ds_read_b128 v[152:155], v14 offset:4608
	ds_read_b128 v[148:151], v14 offset:4640
	ds_read_b128 v[144:147], v14 offset:4672
	ds_read_b128 v[140:143], v14 offset:4704
	ds_read_b128 v[136:139], v0 offset:9280
	ds_read_b128 v[132:135], v0 offset:9312
	ds_read_b128 v[128:131], v0 offset:13888
	ds_read_b128 v[10:13], v0 offset:13920
	s_or_b32 s90, s87, 1
	s_and_b64 s[92:93], s[48:49], s[66:67]
	s_cbranch_scc0 .Lmoba_nf1
	s_cmp_eq_u32 s90, s84
	s_cbranch_scc1 .Lmoba_nf1
	s_cmp_eq_u32 s90, s85
	s_cbranch_scc1 .Lmoba_nf1
	s_waitcnt lgkmcnt(4)
	v_mfma_f32_32x32x16_bf16 v[80:95], v[152:155], v[96:99], v[196:211]
	v_mfma_f32_32x32x16_bf16 v[80:95], v[148:151], v[100:103], v[80:95]
	v_mfma_f32_32x32x16_bf16 v[80:95], v[144:147], v[104:107], v[80:95]
	v_mfma_f32_32x32x16_bf16 v[80:95], v[140:143], v[108:111], v[80:95]
	v_mfma_f32_32x32x16_bf16 v[228:243], v[152:155], v[112:115], v[212:227]
	v_mfma_f32_32x32x16_bf16 v[228:243], v[148:151], v[116:119], v[228:243]
	v_mfma_f32_32x32x16_bf16 v[228:243], v[144:147], v[120:123], v[228:243]
	v_mfma_f32_32x32x16_bf16 v[228:243], v[140:143], v[124:127], v[228:243]
	s_nop 7
	v_exp_f32_e32 v80, v80
	v_exp_f32_e32 v81, v81
	v_exp_f32_e32 v82, v82
	v_exp_f32_e32 v83, v83
	v_exp_f32_e32 v84, v84
	v_exp_f32_e32 v85, v85
	v_exp_f32_e32 v86, v86
	v_exp_f32_e32 v87, v87
	v_exp_f32_e32 v88, v88
	v_exp_f32_e32 v89, v89
	v_exp_f32_e32 v90, v90
	v_exp_f32_e32 v91, v91
	v_exp_f32_e32 v92, v92
	v_exp_f32_e32 v93, v93
	v_exp_f32_e32 v94, v94
	v_exp_f32_e32 v95, v95
	v_exp_f32_e32 v228, v228
	v_add_f32_e32 v186, v80, v186
	v_exp_f32_e32 v229, v229
	v_add_f32_e32 v186, v81, v186
	v_exp_f32_e32 v230, v230
	v_add_f32_e32 v186, v82, v186
	v_exp_f32_e32 v231, v231
	v_add_f32_e32 v186, v83, v186
	v_exp_f32_e32 v232, v232
	v_add_f32_e32 v186, v84, v186
	v_exp_f32_e32 v233, v233
	v_add_f32_e32 v186, v85, v186
	v_exp_f32_e32 v234, v234
	v_add_f32_e32 v186, v86, v186
	v_exp_f32_e32 v235, v235
	v_add_f32_e32 v186, v87, v186
	v_exp_f32_e32 v236, v236
	v_add_f32_e32 v186, v88, v186
	v_exp_f32_e32 v237, v237
	v_add_f32_e32 v186, v89, v186
	v_exp_f32_e32 v238, v238
	v_add_f32_e32 v186, v90, v186
	v_exp_f32_e32 v239, v239
	v_add_f32_e32 v186, v91, v186
	v_exp_f32_e32 v240, v240
	v_add_f32_e32 v186, v92, v186
	v_exp_f32_e32 v241, v241
	v_add_f32_e32 v186, v93, v186
	v_exp_f32_e32 v242, v242
	v_add_f32_e32 v186, v94, v186
	v_exp_f32_e32 v243, v243
	v_add_f32_e32 v186, v95, v186
	s_waitcnt lgkmcnt(0)
	v_cvt_pk_bf16_f32 v80, v80, v81
	v_cvt_pk_bf16_f32 v81, v82, v83
	v_cvt_pk_bf16_f32 v82, v84, v85
	v_cvt_pk_bf16_f32 v83, v86, v87
	v_cvt_pk_bf16_f32 v84, v88, v89
	v_cvt_pk_bf16_f32 v85, v90, v91
	v_cvt_pk_bf16_f32 v86, v92, v93
	v_cvt_pk_bf16_f32 v87, v94, v95
	v_mfma_f32_32x32x16_bf16 v[64:79], v[136:139], v[80:83], v[64:79]
	v_add_f32_e32 v170, v228, v170
	v_add_f32_e32 v170, v229, v170
	v_add_f32_e32 v170, v230, v170
	v_add_f32_e32 v170, v231, v170
	v_mfma_f32_32x32x16_bf16 v[48:63], v[128:131], v[80:83], v[48:63]
	v_add_f32_e32 v170, v232, v170
	v_add_f32_e32 v170, v233, v170
	v_add_f32_e32 v170, v234, v170
	v_add_f32_e32 v170, v235, v170
	v_mfma_f32_32x32x16_bf16 v[64:79], v[132:135], v[84:87], v[64:79]
	v_add_f32_e32 v170, v236, v170
	v_add_f32_e32 v170, v237, v170
	v_add_f32_e32 v170, v238, v170
	v_add_f32_e32 v170, v239, v170
	v_mfma_f32_32x32x16_bf16 v[48:63], v[10:13], v[84:87], v[48:63]
	v_add_f32_e32 v170, v240, v170
	v_add_f32_e32 v170, v241, v170
	v_add_f32_e32 v170, v242, v170
	v_add_f32_e32 v170, v243, v170
	v_cvt_pk_bf16_f32 v228, v228, v229
	v_cvt_pk_bf16_f32 v229, v230, v231
	v_cvt_pk_bf16_f32 v230, v232, v233
	v_cvt_pk_bf16_f32 v231, v234, v235
	v_cvt_pk_bf16_f32 v232, v236, v237
	v_cvt_pk_bf16_f32 v233, v238, v239
	v_cvt_pk_bf16_f32 v234, v240, v241
	v_cvt_pk_bf16_f32 v235, v242, v243
	v_mfma_f32_32x32x16_bf16 v[32:47], v[136:139], v[228:231], v[32:47]
	v_mfma_f32_32x32x16_bf16 v[16:31], v[128:131], v[228:231], v[16:31]
	v_mfma_f32_32x32x16_bf16 v[32:47], v[132:135], v[232:235], v[32:47]
	v_mfma_f32_32x32x16_bf16 v[16:31], v[10:13], v[232:235], v[16:31]
	s_branch .LBB0_403
.Lmoba_nf1:
	s_and_saveexec_b64 s[68:69], s[48:49]
	s_cbranch_execz .LBB0_398
	s_cmp_lg_u32 s90, s84
	s_waitcnt lgkmcnt(7)
	v_mfma_f32_32x32x16_bf16 v[80:95], v[152:155], v[96:99], v[196:211]
	s_waitcnt lgkmcnt(6)
	v_mfma_f32_32x32x16_bf16 v[80:95], v[148:151], v[100:103], v[80:95]
	s_waitcnt lgkmcnt(5)
	v_mfma_f32_32x32x16_bf16 v[80:95], v[144:147], v[104:107], v[80:95]
	s_waitcnt lgkmcnt(4)
	v_mfma_f32_32x32x16_bf16 v[80:95], v[140:143], v[108:111], v[80:95]
	s_nop 11
	v_exp_f32_e32 v15, v80
	v_exp_f32_e32 v80, v81
	v_exp_f32_e32 v81, v82
	v_exp_f32_e32 v82, v83
	v_exp_f32_e32 v188, v84
	v_exp_f32_e32 v85, v85
	v_exp_f32_e32 v190, v86
	v_exp_f32_e32 v192, v87
	v_exp_f32_e32 v83, v88
	v_exp_f32_e32 v84, v89
	v_exp_f32_e32 v86, v90
	v_exp_f32_e32 v87, v91
	v_exp_f32_e32 v88, v92
	v_exp_f32_e32 v89, v93
	v_exp_f32_e32 v90, v94
	v_exp_f32_e32 v91, v95
	s_cbranch_scc1 .LBB0_397
	v_cndmask_b32_e64 v92, v15, 0, s[12:13]
	v_cndmask_b32_e64 v15, v92, v15, s[14:15]
	v_cndmask_b32_e64 v92, v83, 0, s[28:29]
	v_cndmask_b32_e64 v80, 0, v80, s[14:15]
	v_cndmask_b32_e64 v81, v81, 0, s[16:17]
	v_cndmask_b32_e64 v82, v82, 0, s[18:19]
	v_cndmask_b32_e64 v188, v188, 0, s[20:21]
	v_cndmask_b32_e64 v85, v85, 0, s[22:23]
	v_cndmask_b32_e64 v190, v190, 0, s[24:25]
	v_cndmask_b32_e64 v192, v192, 0, s[26:27]
	v_cndmask_b32_e64 v83, v92, v83, s[30:31]
	v_cndmask_b32_e64 v84, 0, v84, s[30:31]
	v_cndmask_b32_e64 v86, v86, 0, s[34:35]
	v_cndmask_b32_e64 v87, v87, 0, s[36:37]
	v_cndmask_b32_e64 v88, v88, 0, s[38:39]
	v_cndmask_b32_e64 v89, v89, 0, s[40:41]
	v_cndmask_b32_e64 v90, v90, 0, s[42:43]
	v_cndmask_b32_e64 v91, v91, 0, s[44:45]

; #define LAS __attribute__((address_space(3)))
; DI f32x16 mfma32(bf16x8 a, bf16x8 b, f32x16 c) { return __builtin_amdgcn_mfma_f32_32x32x16_bf16(a, b, c, 0, 0, 0); }
; DI float ex2(float x) { return __builtin_amdgcn_exp2f(x); }
; template <int MODE>
; DI void sub_tile(const bf16x8 (&kf)[4], const bf16x8 (&vf)[2][2], const bf16x8 (&qf)[4], f32x16& o0, f32x16& o1, float& l, bool diag, float offs, float fm, const LAS float* fsp, int r, int h) {
;     ...
;     if (MODE == 2) {
; #pragma unroll
;         for (int i = 0; i < 16; ++i) x[i] = offs;
; #pragma unroll
;         for (int sp = 0; sp < 4; ++sp) x = mfma32(kf[sp], qf[sp], x);
; #pragma unroll
;         for (int i = 0; i < 16; ++i) p[i] = ex2(x[i]);
;     } else {
;         x = qk_tile(kf, qf);
; #pragma unroll
;         for (int g = 0; g < 4; ++g) {
;             const f32x4 fs = *(const LAS f32x4*)(fsp + 16 * (g >> 1) + 8 * h + 4 * (g & 1));
; #pragma unroll
;             for (int e = 0; e < 4; ++e) p[4 * g + e] = ex2(x[4 * g + e] + (fm - fs[e]));
;         }
;     }
;     if (diag) {
; #pragma unroll
;         for (int i = 0; i < 16; ++i) if (kidx(i, h) > r) p[i] = 0.f;
;     }
; template <int MODE>
; DI void attn_wg2_item(const bf16_t* Qm, const bf16_t* Km, const bf16_t* Vtm, const float* Fb, const float* KMPb, const bf16_t* G, bf16_t* Y, int bh, int qb2, int halfq, int mixer, float Mb, LAS unsigned char* lds, int tid, int wave, int lane) {
;     ...
;                 if (actB) sub_tile<MODE>(kf, vf, qfB, oB0, oB1, lB, tau == qtB, offB, fmB, fsp, r, h);
.LBB0_398:
	s_or_b64 exec, exec, s[68:69]
	s_and_saveexec_b64 s[68:69], s[66:67]
	s_cbranch_execz .LBB0_402
	s_cmp_lg_u32 s90, s85
	s_waitcnt lgkmcnt(7)
	v_mfma_f32_32x32x16_bf16 v[80:95], v[152:155], v[112:115], v[212:227]
	s_waitcnt lgkmcnt(6)
	v_mfma_f32_32x32x16_bf16 v[80:95], v[148:151], v[116:119], v[80:95]
	s_waitcnt lgkmcnt(5)
	v_mfma_f32_32x32x16_bf16 v[80:95], v[144:147], v[120:123], v[80:95]
	s_waitcnt lgkmcnt(4)
	v_mfma_f32_32x32x16_bf16 v[80:95], v[140:143], v[124:127], v[80:95]
	s_nop 11
	v_exp_f32_e32 v144, v80
	v_exp_f32_e32 v145, v81
	v_exp_f32_e32 v140, v82
	v_exp_f32_e32 v141, v83
	v_exp_f32_e32 v142, v84
	v_exp_f32_e32 v143, v85
	v_exp_f32_e32 v86, v86
	v_exp_f32_e32 v87, v87
	v_exp_f32_e32 v88, v88
	v_exp_f32_e32 v15, v89
	v_exp_f32_e32 v80, v90
	v_exp_f32_e32 v81, v91
	v_exp_f32_e32 v82, v92
	v_exp_f32_e32 v83, v93
	v_exp_f32_e32 v84, v94
	v_exp_f32_e32 v85, v95
	s_cbranch_scc1 .LBB0_401
	v_cndmask_b32_e64 v89, v144, 0, s[12:13]
	v_cndmask_b32_e64 v144, v89, v144, s[14:15]
	v_cndmask_b32_e64 v89, v88, 0, s[28:29]
	v_cndmask_b32_e64 v145, 0, v145, s[14:15]
	v_cndmask_b32_e64 v140, v140, 0, s[16:17]
	v_cndmask_b32_e64 v141, v141, 0, s[18:19]
	v_cndmask_b32_e64 v142, v142, 0, s[20:21]
	v_cndmask_b32_e64 v143, v143, 0, s[22:23]
	v_cndmask_b32_e64 v86, v86, 0, s[24:25]
	v_cndmask_b32_e64 v87, v87, 0, s[26:27]
	v_cndmask_b32_e64 v88, v89, v88, s[30:31]
	v_cndmask_b32_e64 v15, 0, v15, s[30:31]
	v_cndmask_b32_e64 v80, v80, 0, s[34:35]
	v_cndmask_b32_e64 v81, v81, 0, s[36:37]
	v_cndmask_b32_e64 v82, v82, 0, s[38:39]
	v_cndmask_b32_e64 v83, v83, 0, s[40:41]
	v_cndmask_b32_e64 v84, v84, 0, s[42:43]
	v_cndmask_b32_e64 v85, v85, 0, s[44:45]

; template <int MODE>
; DI void sub_tile(const bf16x8 (&kf)[4], const bf16x8 (&vf)[2][2], const bf16x8 (&qf)[4], f32x16& o0, f32x16& o1, float& l, bool diag, float offs, float fm, const LAS float* fsp, int r, int h) {
;     f32x16 x;
;     float p[16];
;     if (MODE == 2) {
; #pragma unroll
;         for (int i = 0; i < 16; ++i) x[i] = offs;
; #pragma unroll
;         for (int sp = 0; sp < 4; ++sp) x = mfma32(kf[sp], qf[sp], x);
; #pragma unroll
;         for (int i = 0; i < 16; ++i) p[i] = ex2(x[i]);
;     } else {
;         x = qk_tile(kf, qf);
; #pragma unroll
;         for (int g = 0; g < 4; ++g) {
;             const f32x4 fs = *(const LAS f32x4*)(fsp + 16 * (g >> 1) + 8 * h + 4 * (g & 1));
; #pragma unroll
;             for (int e = 0; e < 4; ++e) p[4 * g + e] = ex2(x[4 * g + e] + (fm - fs[e]));
;         }
;     }
;     if (diag) {
; #pragma unroll
;         for (int i = 0; i < 16; ++i) if (kidx(i, h) > r) p[i] = 0.f;
;     }
; #pragma unroll
; template <int MODE>
; DI void attn_wg2_item(const bf16_t* Qm, const bf16_t* Km, const bf16_t* Vtm, const float* Fb, const float* KMPb, const bf16_t* G, bf16_t* Y, int bh, int qb2, int halfq, int mixer, float Mb, LAS unsigned char* lds, int tid, int wave, int lane) {
;     ...
;             const int tau = cur * 2 + kk, nb = tau >> 3;
;             bool actA = tau <= qtA, actB = tau <= qtB;
;             if (MODE == 2) { actA = actA && ((visA >> nb) & 1u); actB = actB && ((visB >> nb) & 1u); }
;             if (actA || actB) {
;                 bf16x8 kf[4], vf[2][2];
; #pragma unroll
;                 for (int sp = 0; sp < 4; ++sp) kf[sp] = *(LAS bf16x8*)(lb + kra + kk * 32 * 144 + sp * 32);
; #pragma unroll
;                 for (int dd = 0; dd < 2; ++dd)
; #pragma unroll
;                     for (int s = 0; s < 2; ++s) vf[dd][s] = *(LAS bf16x8*)(lb + vra + dd * 32 * 144 + kk * 64 + s * 32);
;                 float offA = mb2, offB = mb2;
;                 if (MODE == 2) { offA = ((nb == qblkA) || ((selA >> nb) & 1u)) ? mb2 : NEGI; offB = ((nb == qblkB) || ((selB >> nb) & 1u)) ? mb2 : NEGI; }
;                 const LAS float* fsp = (const LAS float*)(lb + AW_F) + kk * 32;
;                 if (actA) sub_tile<MODE>(kf, vf, qfA, oA0, oA1, lA, tau == qtA, offA, fmA, fsp, r, h);
;                 if (actB) sub_tile<MODE>(kf, vf, qfB, oB0, oB1, lB, tau == qtB, offB, fmB, fsp, r, h);
.LBB0_403:
	s_or_b64 exec, exec, s[64:65]
	s_cmp_le_i32 s87, s84
	s_cselect_b64 s[48:49], -1, 0
	s_cmp_le_i32 s87, s85
	s_cselect_b64 s[64:65], -1, 0
	s_and_b64 s[66:67], s[48:49], vcc
	s_and_b64 s[48:49], s[64:65], s[46:47]
	s_or_b64 s[64:65], s[66:67], s[48:49]
	s_and_saveexec_b64 s[46:47], s[64:65]
	s_cbranch_execz .LBB0_413
	s_waitcnt lgkmcnt(7)
	ds_read_b128 v[152:155], v14
	s_waitcnt lgkmcnt(7)
	ds_read_b128 v[148:151], v14 offset:32
	s_waitcnt lgkmcnt(7)
	ds_read_b128 v[144:147], v14 offset:64
	s_waitcnt lgkmcnt(7)
	ds_read_b128 v[140:143], v14 offset:96
	s_waitcnt lgkmcnt(7)
	ds_read_b128 v[136:139], v0 offset:9216
	s_waitcnt lgkmcnt(7)
	ds_read_b128 v[132:135], v0 offset:9248
	s_waitcnt lgkmcnt(7)
	ds_read_b128 v[128:131], v0 offset:13824
	s_waitcnt lgkmcnt(7)
	ds_read_b128 v[10:13], v0 offset:13856
	s_and_b64 s[92:93], s[48:49], s[66:67]
	s_cbranch_scc0 .Lmoba_nf0
	s_cmp_eq_u32 s87, s84
	s_cbranch_scc1 .Lmoba_nf0
	s_cmp_eq_u32 s87, s85
	s_cbranch_scc1 .Lmoba_nf0
	s_waitcnt lgkmcnt(4)
	v_mfma_f32_32x32x16_bf16 v[80:95], v[152:155], v[96:99], v[196:211]
	v_mfma_f32_32x32x16_bf16 v[80:95], v[148:151], v[100:103], v[80:95]
	v_mfma_f32_32x32x16_bf16 v[80:95], v[144:147], v[104:107], v[80:95]
	v_mfma_f32_32x32x16_bf16 v[80:95], v[140:143], v[108:111], v[80:95]
	v_mfma_f32_32x32x16_bf16 v[228:243], v[152:155], v[112:115], v[212:227]
	v_mfma_f32_32x32x16_bf16 v[228:243], v[148:151], v[116:119], v[228:243]
	v_mfma_f32_32x32x16_bf16 v[228:243], v[144:147], v[120:123], v[228:243]
	v_mfma_f32_32x32x16_bf16 v[228:243], v[140:143], v[124:127], v[228:243]
	s_nop 7
	v_exp_f32_e32 v80, v80
	v_exp_f32_e32 v81, v81
	v_exp_f32_e32 v82, v82
	v_exp_f32_e32 v83, v83
	v_exp_f32_e32 v84, v84
	v_exp_f32_e32 v85, v85
	v_exp_f32_e32 v86, v86
	v_exp_f32_e32 v87, v87
	v_exp_f32_e32 v88, v88
	v_exp_f32_e32 v89, v89
	v_exp_f32_e32 v90, v90
	v_exp_f32_e32 v91, v91
	v_exp_f32_e32 v92, v92
	v_exp_f32_e32 v93, v93
	v_exp_f32_e32 v94, v94
	v_exp_f32_e32 v95, v95
	v_exp_f32_e32 v228, v228
	v_add_f32_e32 v186, v80, v186
	v_exp_f32_e32 v229, v229
	v_add_f32_e32 v186, v81, v186
	v_exp_f32_e32 v230, v230
	v_add_f32_e32 v186, v82, v186
	v_exp_f32_e32 v231, v231
	v_add_f32_e32 v186, v83, v186
	v_exp_f32_e32 v232, v232
	v_add_f32_e32 v186, v84, v186
	v_exp_f32_e32 v233, v233
	v_add_f32_e32 v186, v85, v186
	v_exp_f32_e32 v234, v234
	v_add_f32_e32 v186, v86, v186
	v_exp_f32_e32 v235, v235
	v_add_f32_e32 v186, v87, v186
	v_exp_f32_e32 v236, v236
	v_add_f32_e32 v186, v88, v186
	v_exp_f32_e32 v237, v237
	v_add_f32_e32 v186, v89, v186
	v_exp_f32_e32 v238, v238
	v_add_f32_e32 v186, v90, v186
	v_exp_f32_e32 v239, v239
	v_add_f32_e32 v186, v91, v186
	v_exp_f32_e32 v240, v240
	v_add_f32_e32 v186, v92, v186
	v_exp_f32_e32 v241, v241
	v_add_f32_e32 v186, v93, v186
	v_exp_f32_e32 v242, v242
	v_add_f32_e32 v186, v94, v186
	v_exp_f32_e32 v243, v243
	v_add_f32_e32 v186, v95, v186
	s_waitcnt lgkmcnt(0)
	v_cvt_pk_bf16_f32 v80, v80, v81
	v_cvt_pk_bf16_f32 v81, v82, v83
	v_cvt_pk_bf16_f32 v82, v84, v85
	v_cvt_pk_bf16_f32 v83, v86, v87
	v_cvt_pk_bf16_f32 v84, v88, v89
	v_cvt_pk_bf16_f32 v85, v90, v91
	v_cvt_pk_bf16_f32 v86, v92, v93
	v_cvt_pk_bf16_f32 v87, v94, v95
	v_mfma_f32_32x32x16_bf16 v[64:79], v[136:139], v[80:83], v[64:79]
	v_add_f32_e32 v170, v228, v170
	v_add_f32_e32 v170, v229, v170
	v_add_f32_e32 v170, v230, v170
	v_add_f32_e32 v170, v231, v170
	v_mfma_f32_32x32x16_bf16 v[48:63], v[128:131], v[80:83], v[48:63]
	v_add_f32_e32 v170, v232, v170
	v_add_f32_e32 v170, v233, v170
	v_add_f32_e32 v170, v234, v170
	v_add_f32_e32 v170, v235, v170
	v_mfma_f32_32x32x16_bf16 v[64:79], v[132:135], v[84:87], v[64:79]
	v_add_f32_e32 v170, v236, v170
	v_add_f32_e32 v170, v237, v170
	v_add_f32_e32 v170, v238, v170
	v_add_f32_e32 v170, v239, v170
	v_mfma_f32_32x32x16_bf16 v[48:63], v[10:13], v[84:87], v[48:63]
	v_add_f32_e32 v170, v240, v170
	v_add_f32_e32 v170, v241, v170
	v_add_f32_e32 v170, v242, v170
	v_add_f32_e32 v170, v243, v170
	v_cvt_pk_bf16_f32 v228, v228, v229
	v_cvt_pk_bf16_f32 v229, v230, v231
	v_cvt_pk_bf16_f32 v230, v232, v233
	v_cvt_pk_bf16_f32 v231, v234, v235
	v_cvt_pk_bf16_f32 v232, v236, v237
	v_cvt_pk_bf16_f32 v233, v238, v239
	v_cvt_pk_bf16_f32 v234, v240, v241
	v_cvt_pk_bf16_f32 v235, v242, v243
	v_mfma_f32_32x32x16_bf16 v[32:47], v[136:139], v[228:231], v[32:47]
	v_mfma_f32_32x32x16_bf16 v[16:31], v[128:131], v[228:231], v[16:31]
	v_mfma_f32_32x32x16_bf16 v[32:47], v[132:135], v[232:235], v[32:47]
	v_mfma_f32_32x32x16_bf16 v[16:31], v[10:13], v[232:235], v[16:31]
	s_branch .LBB0_413
.Lmoba_nf0:
	s_and_saveexec_b64 s[64:65], s[66:67]
	s_cbranch_execz .LBB0_408
	s_cmp_lg_u32 s87, s84
	s_waitcnt lgkmcnt(7)
	v_mfma_f32_32x32x16_bf16 v[80:95], v[152:155], v[96:99], v[196:211]
	s_waitcnt lgkmcnt(6)
	v_mfma_f32_32x32x16_bf16 v[80:95], v[148:151], v[100:103], v[80:95]
	s_waitcnt lgkmcnt(5)
	v_mfma_f32_32x32x16_bf16 v[80:95], v[144:147], v[104:107], v[80:95]
	s_waitcnt lgkmcnt(4)
	v_mfma_f32_32x32x16_bf16 v[80:95], v[140:143], v[108:111], v[80:95]
	s_nop 11
	v_exp_f32_e32 v0, v80
	v_exp_f32_e32 v14, v81
	v_exp_f32_e32 v15, v82
	v_exp_f32_e32 v80, v83
	v_exp_f32_e32 v83, v84
	v_exp_f32_e32 v84, v85
	v_exp_f32_e32 v188, v86
	v_exp_f32_e32 v87, v87
	v_exp_f32_e32 v81, v88
	v_exp_f32_e32 v82, v89
	v_exp_f32_e32 v85, v90
	v_exp_f32_e32 v86, v91
	v_exp_f32_e32 v88, v92
	v_exp_f32_e32 v89, v93
	v_exp_f32_e32 v90, v94
	v_exp_f32_e32 v91, v95
	s_cbranch_scc1 .LBB0_407
	v_cndmask_b32_e64 v92, v0, 0, s[12:13]
	v_cndmask_b32_e64 v0, v92, v0, s[14:15]
	v_cndmask_b32_e64 v92, v81, 0, s[28:29]
	v_cndmask_b32_e64 v14, 0, v14, s[14:15]
	v_cndmask_b32_e64 v15, v15, 0, s[16:17]
	v_cndmask_b32_e64 v80, v80, 0, s[18:19]
	v_cndmask_b32_e64 v83, v83, 0, s[20:21]
	v_cndmask_b32_e64 v84, v84, 0, s[22:23]
	v_cndmask_b32_e64 v188, v188, 0, s[24:25]
	v_cndmask_b32_e64 v87, v87, 0, s[26:27]
	v_cndmask_b32_e64 v81, v92, v81, s[30:31]
	v_cndmask_b32_e64 v82, 0, v82, s[30:31]
	v_cndmask_b32_e64 v85, v85, 0, s[34:35]
	v_cndmask_b32_e64 v86, v86, 0, s[36:37]
	v_cndmask_b32_e64 v88, v88, 0, s[38:39]
	v_cndmask_b32_e64 v89, v89, 0, s[40:41]
	v_cndmask_b32_e64 v90, v90, 0, s[42:43]
	v_cndmask_b32_e64 v91, v91, 0, s[44:45]

; #define LAS __attribute__((address_space(3)))
; DI f32x16 mfma32(bf16x8 a, bf16x8 b, f32x16 c) { return __builtin_amdgcn_mfma_f32_32x32x16_bf16(a, b, c, 0, 0, 0); }
; DI float ex2(float x) { return __builtin_amdgcn_exp2f(x); }
; template <int MODE>
; DI void sub_tile(const bf16x8 (&kf)[4], const bf16x8 (&vf)[2][2], const bf16x8 (&qf)[4], f32x16& o0, f32x16& o1, float& l, bool diag, float offs, float fm, const LAS float* fsp, int r, int h) {
;     ...
;     if (MODE == 2) {
; #pragma unroll
;         for (int i = 0; i < 16; ++i) x[i] = offs;
; #pragma unroll
;         for (int sp = 0; sp < 4; ++sp) x = mfma32(kf[sp], qf[sp], x);
; #pragma unroll
;         for (int i = 0; i < 16; ++i) p[i] = ex2(x[i]);
;     } else {
;         x = qk_tile(kf, qf);
; #pragma unroll
;         for (int g = 0; g < 4; ++g) {
;             const f32x4 fs = *(const LAS f32x4*)(fsp + 16 * (g >> 1) + 8 * h + 4 * (g & 1));
; #pragma unroll
;             for (int e = 0; e < 4; ++e) p[4 * g + e] = ex2(x[4 * g + e] + (fm - fs[e]));
;         }
;     }
;     if (diag) {
; #pragma unroll
;         for (int i = 0; i < 16; ++i) if (kidx(i, h) > r) p[i] = 0.f;
;     }
; template <int MODE>
; DI void attn_wg2_item(const bf16_t* Qm, const bf16_t* Km, const bf16_t* Vtm, const float* Fb, const float* KMPb, const bf16_t* G, bf16_t* Y, int bh, int qb2, int halfq, int mixer, float Mb, LAS unsigned char* lds, int tid, int wave, int lane) {
;     ...
;                 if (actB) sub_tile<MODE>(kf, vf, qfB, oB0, oB1, lB, tau == qtB, offB, fmB, fsp, r, h);
.LBB0_408:
	s_or_b64 exec, exec, s[64:65]
	s_and_saveexec_b64 s[64:65], s[48:49]
	s_cbranch_execz .LBB0_412
	s_cmp_lg_u32 s87, s85
	s_waitcnt lgkmcnt(7)
	v_mfma_f32_32x32x16_bf16 v[80:95], v[152:155], v[112:115], v[212:227]
	s_waitcnt lgkmcnt(6)
	v_mfma_f32_32x32x16_bf16 v[80:95], v[148:151], v[116:119], v[80:95]
	s_waitcnt lgkmcnt(5)
	v_mfma_f32_32x32x16_bf16 v[80:95], v[144:147], v[120:123], v[80:95]
	s_waitcnt lgkmcnt(4)
	v_mfma_f32_32x32x16_bf16 v[80:95], v[140:143], v[124:127], v[80:95]
	s_nop 11
	v_exp_f32_e32 v142, v80
	v_exp_f32_e32 v143, v81
	v_exp_f32_e32 v140, v82
	v_exp_f32_e32 v141, v83
	v_exp_f32_e32 v84, v84
	v_exp_f32_e32 v85, v85
	v_exp_f32_e32 v86, v86
	v_exp_f32_e32 v87, v87
	v_exp_f32_e32 v88, v88
	v_exp_f32_e32 v0, v89
	v_exp_f32_e32 v14, v90
	v_exp_f32_e32 v15, v91
	v_exp_f32_e32 v80, v92
	v_exp_f32_e32 v81, v93
	v_exp_f32_e32 v82, v94
	v_exp_f32_e32 v83, v95
	s_cbranch_scc1 .LBB0_411
	v_cndmask_b32_e64 v89, v142, 0, s[12:13]
	v_cndmask_b32_e64 v142, v89, v142, s[14:15]
	v_cndmask_b32_e64 v89, v88, 0, s[28:29]
	v_cndmask_b32_e64 v143, 0, v143, s[14:15]
	v_cndmask_b32_e64 v140, v140, 0, s[16:17]
	v_cndmask_b32_e64 v141, v141, 0, s[18:19]
	v_cndmask_b32_e64 v84, v84, 0, s[20:21]
	v_cndmask_b32_e64 v85, v85, 0, s[22:23]
	v_cndmask_b32_e64 v86, v86, 0, s[24:25]
	v_cndmask_b32_e64 v87, v87, 0, s[26:27]
	v_cndmask_b32_e64 v88, v89, v88, s[30:31]
	v_cndmask_b32_e64 v0, 0, v0, s[30:31]
	v_cndmask_b32_e64 v14, v14, 0, s[34:35]
	v_cndmask_b32_e64 v15, v15, 0, s[36:37]
	v_cndmask_b32_e64 v80, v80, 0, s[38:39]
	v_cndmask_b32_e64 v81, v81, 0, s[40:41]
	v_cndmask_b32_e64 v82, v82, 0, s[42:43]
	v_cndmask_b32_e64 v83, v83, 0, s[44:45]
